# v12 + multi-tile GEMM phases (w_in, gate/up): keep the two wave-halves staggered across tile boundaries (epilogue alignment barriers only for the last tile) so one half's epilogue overlaps the other h
# baseline (speedup 1.0000x reference)
.LBB0_295:
	ds_read_b128 v[146:149], v155
	ds_read_b128 v[160:163], v155 offset:1024
	ds_read_b128 v[164:167], v155 offset:2048
	ds_read_b128 v[168:171], v155 offset:3072
	ds_read_b128 v[172:175], v156
	ds_read_b128 v[176:179], v156 offset:1024
	ds_read_b128 v[180:183], v156 offset:2048
	ds_read_b128 v[184:187], v156 offset:3072
	s_add_u32 s23, s64, 0xfffc0080
	s_addc_u32 s33, s65, -1
	s_cmp_eq_u32 s92, 12
	s_cselect_b32 s73, s20, s33
	s_cselect_b32 s72, s21, s23
	s_cselect_b32 s71, s19, s91
	s_cselect_b32 s70, s55, s90
	s_add_i32 m0, s76, 0xc000
	ds_read_b128 v[188:191], v157
	ds_read_b128 v[192:195], v157 offset:1024
	ds_read_b128 v[196:199], v157 offset:2048
	ds_read_b128 v[200:203], v157 offset:3072
	ds_read_b128 v[204:207], v157 offset:4096
	ds_read_b128 v[208:211], v157 offset:5120
	ds_read_b128 v[212:215], v157 offset:6144
	ds_read_b128 v[216:219], v157 offset:7168
	global_load_lds_dwordx4 v138, s[64:65]
	s_add_i32 m0, s76, 0xe000
	s_nop 0
	global_load_lds_dwordx4 v140, s[64:65]
	s_waitcnt vmcnt(8)
	s_waitcnt lgkmcnt(0)
	s_barrier
	s_setprio 1
	v_mfma_f32_16x16x32_bf16 v[124:127], v[146:149], v[188:191], v[124:127]
	v_mfma_f32_16x16x32_bf16 v[120:123], v[164:167], v[188:191], v[120:123]
	v_mfma_f32_16x16x32_bf16 v[108:111], v[146:149], v[196:199], v[108:111]
	v_mfma_f32_16x16x32_bf16 v[104:107], v[164:167], v[196:199], v[104:107]
	v_mfma_f32_16x16x32_bf16 v[92:95], v[146:149], v[204:207], v[92:95]
	v_mfma_f32_16x16x32_bf16 v[88:91], v[164:167], v[204:207], v[88:91]
	v_mfma_f32_16x16x32_bf16 v[76:79], v[146:149], v[212:215], v[76:79]
	v_mfma_f32_16x16x32_bf16 v[72:75], v[164:167], v[212:215], v[72:75]
	v_mfma_f32_16x16x32_bf16 v[124:127], v[160:163], v[192:195], v[124:127]
	v_mfma_f32_16x16x32_bf16 v[120:123], v[168:171], v[192:195], v[120:123]
	v_mfma_f32_16x16x32_bf16 v[108:111], v[160:163], v[200:203], v[108:111]
	v_mfma_f32_16x16x32_bf16 v[104:107], v[168:171], v[200:203], v[104:107]
	v_mfma_f32_16x16x32_bf16 v[92:95], v[160:163], v[208:211], v[92:95]
	v_mfma_f32_16x16x32_bf16 v[88:91], v[168:171], v[208:211], v[88:91]
	v_mfma_f32_16x16x32_bf16 v[76:79], v[160:163], v[216:219], v[76:79]
	v_mfma_f32_16x16x32_bf16 v[72:75], v[168:171], v[216:219], v[72:75]
	v_mfma_f32_16x16x32_bf16 v[116:119], v[172:175], v[188:191], v[116:119]
	v_mfma_f32_16x16x32_bf16 v[112:115], v[180:183], v[188:191], v[112:115]
	v_mfma_f32_16x16x32_bf16 v[100:103], v[172:175], v[196:199], v[100:103]
	v_mfma_f32_16x16x32_bf16 v[96:99], v[180:183], v[196:199], v[96:99]
	v_mfma_f32_16x16x32_bf16 v[84:87], v[172:175], v[204:207], v[84:87]
	v_mfma_f32_16x16x32_bf16 v[80:83], v[180:183], v[204:207], v[80:83]
	v_mfma_f32_16x16x32_bf16 v[68:71], v[172:175], v[212:215], v[68:71]
	v_mfma_f32_16x16x32_bf16 v[64:67], v[180:183], v[212:215], v[64:67]
	v_mfma_f32_16x16x32_bf16 v[116:119], v[176:179], v[192:195], v[116:119]
	v_mfma_f32_16x16x32_bf16 v[112:115], v[184:187], v[192:195], v[112:115]
	v_mfma_f32_16x16x32_bf16 v[100:103], v[176:179], v[200:203], v[100:103]
	v_mfma_f32_16x16x32_bf16 v[96:99], v[184:187], v[200:203], v[96:99]
	v_mfma_f32_16x16x32_bf16 v[84:87], v[176:179], v[208:211], v[84:87]
	v_mfma_f32_16x16x32_bf16 v[80:83], v[184:187], v[208:211], v[80:83]
	v_mfma_f32_16x16x32_bf16 v[68:71], v[176:179], v[216:219], v[68:71]
	v_mfma_f32_16x16x32_bf16 v[64:67], v[184:187], v[216:219], v[64:67]
	s_setprio 0
	s_barrier
	s_add_i32 s23, s85, s74
	s_mov_b32 m0, s23
	ds_read_b128 v[188:191], v157 offset:16384
	ds_read_b128 v[192:195], v157 offset:17408
	ds_read_b128 v[196:199], v157 offset:18432
	ds_read_b128 v[200:203], v157 offset:19456
	ds_read_b128 v[204:207], v157 offset:20480
	ds_read_b128 v[208:211], v157 offset:21504
	ds_read_b128 v[212:215], v157 offset:22528
	ds_read_b128 v[216:219], v157 offset:23552
	global_load_lds_dwordx4 v132, s[70:71]
	s_add_i32 m0, s23, 0x2000
	s_add_u32 s94, s70, 0x40000
	s_addc_u32 s95, s71, 0
	s_add_i32 s23, s86, s74
	global_load_lds_dwordx4 v136, s[70:71]
	s_mov_b32 m0, s23
	s_add_u32 s98, s70, s10
	s_addc_u32 s99, s71, s11
	global_load_lds_dwordx4 v132, s[94:95]
	s_add_i32 m0, s23, 0x2000
	s_add_u32 s100, s72, s10
	s_addc_u32 s101, s73, s11
	global_load_lds_dwordx4 v136, s[94:95]
	s_mov_b32 m0, s76
	s_nop 0
	global_load_lds_dwordx4 v130, s[72:73]
	s_mov_b32 m0, s77
	s_nop 0
	global_load_lds_dwordx4 v134, s[72:73]
	s_waitcnt vmcnt(8)
	s_waitcnt lgkmcnt(0)
	s_barrier
	s_setprio 1
	v_mfma_f32_16x16x32_bf16 v[60:63], v[146:149], v[188:191], v[60:63]
	v_mfma_f32_16x16x32_bf16 v[56:59], v[164:167], v[188:191], v[56:59]
	v_mfma_f32_16x16x32_bf16 v[44:47], v[146:149], v[196:199], v[44:47]
	v_mfma_f32_16x16x32_bf16 v[40:43], v[164:167], v[196:199], v[40:43]
	v_mfma_f32_16x16x32_bf16 v[28:31], v[146:149], v[204:207], v[28:31]
	v_mfma_f32_16x16x32_bf16 v[24:27], v[164:167], v[204:207], v[24:27]
	v_mfma_f32_16x16x32_bf16 v[12:15], v[146:149], v[212:215], v[12:15]
	v_mfma_f32_16x16x32_bf16 v[8:11], v[164:167], v[212:215], v[8:11]
	v_mfma_f32_16x16x32_bf16 v[60:63], v[160:163], v[192:195], v[60:63]
	v_mfma_f32_16x16x32_bf16 v[56:59], v[168:171], v[192:195], v[56:59]
	v_mfma_f32_16x16x32_bf16 v[44:47], v[160:163], v[200:203], v[44:47]
	v_mfma_f32_16x16x32_bf16 v[40:43], v[168:171], v[200:203], v[40:43]
	v_mfma_f32_16x16x32_bf16 v[28:31], v[160:163], v[208:211], v[28:31]
	v_mfma_f32_16x16x32_bf16 v[24:27], v[168:171], v[208:211], v[24:27]
	v_mfma_f32_16x16x32_bf16 v[12:15], v[160:163], v[216:219], v[12:15]
	v_mfma_f32_16x16x32_bf16 v[8:11], v[168:171], v[216:219], v[8:11]
	v_mfma_f32_16x16x32_bf16 v[52:55], v[172:175], v[188:191], v[52:55]
	v_mfma_f32_16x16x32_bf16 v[48:51], v[180:183], v[188:191], v[48:51]
	v_mfma_f32_16x16x32_bf16 v[36:39], v[172:175], v[196:199], v[36:39]
	v_mfma_f32_16x16x32_bf16 v[32:35], v[180:183], v[196:199], v[32:35]
	v_mfma_f32_16x16x32_bf16 v[20:23], v[172:175], v[204:207], v[20:23]
	v_mfma_f32_16x16x32_bf16 v[16:19], v[180:183], v[204:207], v[16:19]
	v_mfma_f32_16x16x32_bf16 v[4:7], v[172:175], v[212:215], v[4:7]
	v_mfma_f32_16x16x32_bf16 v[0:3], v[180:183], v[212:215], v[0:3]
	v_mfma_f32_16x16x32_bf16 v[52:55], v[176:179], v[192:195], v[52:55]
	v_mfma_f32_16x16x32_bf16 v[48:51], v[184:187], v[192:195], v[48:51]
	v_mfma_f32_16x16x32_bf16 v[36:39], v[176:179], v[200:203], v[36:39]
	v_mfma_f32_16x16x32_bf16 v[32:35], v[184:187], v[200:203], v[32:35]
	v_mfma_f32_16x16x32_bf16 v[20:23], v[176:179], v[208:211], v[20:23]
	v_mfma_f32_16x16x32_bf16 v[16:19], v[184:187], v[208:211], v[16:19]
	v_mfma_f32_16x16x32_bf16 v[4:7], v[176:179], v[216:219], v[4:7]
	v_mfma_f32_16x16x32_bf16 v[0:3], v[184:187], v[216:219], v[0:3]
	s_setprio 0
	s_barrier
	s_add_i32 s23, 0, 0x18000
	v_add_u32_e32 v159, s23, v153
	s_add_i32 s33, 0, 0x1c000
	ds_read_b128 v[146:149], v159
	ds_read_b128 v[160:163], v159 offset:1024
	ds_read_b128 v[164:167], v159 offset:2048
	ds_read_b128 v[168:171], v159 offset:3072
	v_add_u32_e32 v159, s33, v153
	ds_read_b128 v[172:175], v159
	ds_read_b128 v[176:179], v159 offset:1024
	ds_read_b128 v[180:183], v159 offset:2048
	ds_read_b128 v[184:187], v159 offset:3072
	s_add_u32 s72, s72, 0x40000
	s_addc_u32 s73, s73, 0
	s_mov_b32 m0, s78
	ds_read_b128 v[188:191], v157 offset:32768
	ds_read_b128 v[192:195], v157 offset:33792
	ds_read_b128 v[196:199], v157 offset:34816
	ds_read_b128 v[200:203], v157 offset:35840
	ds_read_b128 v[204:207], v157 offset:36864
	ds_read_b128 v[208:211], v157 offset:37888
	ds_read_b128 v[212:215], v157 offset:38912
	ds_read_b128 v[216:219], v157 offset:39936
	global_load_lds_dwordx4 v130, s[72:73]
	s_mov_b32 m0, s79
	s_nop 0
	global_load_lds_dwordx4 v134, s[72:73]
	s_waitcnt vmcnt(8)
	s_waitcnt lgkmcnt(0)
	s_barrier
	s_setprio 1
	v_mfma_f32_16x16x32_bf16 v[124:127], v[146:149], v[188:191], v[124:127]
	v_mfma_f32_16x16x32_bf16 v[120:123], v[164:167], v[188:191], v[120:123]
	v_mfma_f32_16x16x32_bf16 v[108:111], v[146:149], v[196:199], v[108:111]
	v_mfma_f32_16x16x32_bf16 v[104:107], v[164:167], v[196:199], v[104:107]
	v_mfma_f32_16x16x32_bf16 v[92:95], v[146:149], v[204:207], v[92:95]
	v_mfma_f32_16x16x32_bf16 v[88:91], v[164:167], v[204:207], v[88:91]
	v_mfma_f32_16x16x32_bf16 v[76:79], v[146:149], v[212:215], v[76:79]
	v_mfma_f32_16x16x32_bf16 v[72:75], v[164:167], v[212:215], v[72:75]
	v_mfma_f32_16x16x32_bf16 v[124:127], v[160:163], v[192:195], v[124:127]
	v_mfma_f32_16x16x32_bf16 v[120:123], v[168:171], v[192:195], v[120:123]
	v_mfma_f32_16x16x32_bf16 v[108:111], v[160:163], v[200:203], v[108:111]
	v_mfma_f32_16x16x32_bf16 v[104:107], v[168:171], v[200:203], v[104:107]
	v_mfma_f32_16x16x32_bf16 v[92:95], v[160:163], v[208:211], v[92:95]
	v_mfma_f32_16x16x32_bf16 v[88:91], v[168:171], v[208:211], v[88:91]
	v_mfma_f32_16x16x32_bf16 v[76:79], v[160:163], v[216:219], v[76:79]
	v_mfma_f32_16x16x32_bf16 v[72:75], v[168:171], v[216:219], v[72:75]
	v_mfma_f32_16x16x32_bf16 v[116:119], v[172:175], v[188:191], v[116:119]
	v_mfma_f32_16x16x32_bf16 v[112:115], v[180:183], v[188:191], v[112:115]
	v_mfma_f32_16x16x32_bf16 v[100:103], v[172:175], v[196:199], v[100:103]
	v_mfma_f32_16x16x32_bf16 v[96:99], v[180:183], v[196:199], v[96:99]
	v_mfma_f32_16x16x32_bf16 v[84:87], v[172:175], v[204:207], v[84:87]
	v_mfma_f32_16x16x32_bf16 v[80:83], v[180:183], v[204:207], v[80:83]
	v_mfma_f32_16x16x32_bf16 v[68:71], v[172:175], v[212:215], v[68:71]
	v_mfma_f32_16x16x32_bf16 v[64:67], v[180:183], v[212:215], v[64:67]
	v_mfma_f32_16x16x32_bf16 v[116:119], v[176:179], v[192:195], v[116:119]
	v_mfma_f32_16x16x32_bf16 v[112:115], v[184:187], v[192:195], v[112:115]
	v_mfma_f32_16x16x32_bf16 v[100:103], v[176:179], v[200:203], v[100:103]
	v_mfma_f32_16x16x32_bf16 v[96:99], v[184:187], v[200:203], v[96:99]
	v_mfma_f32_16x16x32_bf16 v[84:87], v[176:179], v[208:211], v[84:87]
	v_mfma_f32_16x16x32_bf16 v[80:83], v[184:187], v[208:211], v[80:83]
	v_mfma_f32_16x16x32_bf16 v[68:71], v[176:179], v[216:219], v[68:71]
	v_mfma_f32_16x16x32_bf16 v[64:67], v[184:187], v[216:219], v[64:67]
	s_setprio 0
	s_barrier
	s_add_i32 s23, s23, s74
	s_mov_b32 m0, s23
	ds_read_b128 v[188:191], v157 offset:49152
	ds_read_b128 v[192:195], v157 offset:50176
	ds_read_b128 v[196:199], v157 offset:51200
	ds_read_b128 v[200:203], v157 offset:52224
	ds_read_b128 v[204:207], v157 offset:53248
	ds_read_b128 v[208:211], v157 offset:54272
	ds_read_b128 v[212:215], v157 offset:55296
	ds_read_b128 v[216:219], v157 offset:56320
	global_load_lds_dwordx4 v132, s[98:99]
	s_add_i32 m0, s23, 0x2000
	s_add_u32 s70, s70, 0x40080
	s_addc_u32 s71, s71, 0
	s_add_i32 s23, s33, s74
	global_load_lds_dwordx4 v136, s[98:99]
	s_mov_b32 m0, s23
	s_nop 0
	global_load_lds_dwordx4 v132, s[70:71]
	s_add_i32 m0, s23, 0x2000
	s_nop 0
	global_load_lds_dwordx4 v136, s[70:71]
	s_mov_b32 m0, s82
	s_nop 0
	global_load_lds_dwordx4 v130, s[100:101]
	s_mov_b32 m0, s83
	s_nop 0
	global_load_lds_dwordx4 v134, s[100:101]
	s_waitcnt vmcnt(8)
	s_waitcnt lgkmcnt(0)
	s_barrier
	s_setprio 1
	v_mfma_f32_16x16x32_bf16 v[60:63], v[146:149], v[188:191], v[60:63]
	v_mfma_f32_16x16x32_bf16 v[56:59], v[164:167], v[188:191], v[56:59]
	v_mfma_f32_16x16x32_bf16 v[44:47], v[146:149], v[196:199], v[44:47]
	v_mfma_f32_16x16x32_bf16 v[40:43], v[164:167], v[196:199], v[40:43]
	v_mfma_f32_16x16x32_bf16 v[28:31], v[146:149], v[204:207], v[28:31]
	v_mfma_f32_16x16x32_bf16 v[24:27], v[164:167], v[204:207], v[24:27]
	v_mfma_f32_16x16x32_bf16 v[12:15], v[146:149], v[212:215], v[12:15]
	v_mfma_f32_16x16x32_bf16 v[8:11], v[164:167], v[212:215], v[8:11]
	v_mfma_f32_16x16x32_bf16 v[60:63], v[160:163], v[192:195], v[60:63]
	v_mfma_f32_16x16x32_bf16 v[56:59], v[168:171], v[192:195], v[56:59]
	v_mfma_f32_16x16x32_bf16 v[44:47], v[160:163], v[200:203], v[44:47]
	v_mfma_f32_16x16x32_bf16 v[40:43], v[168:171], v[200:203], v[40:43]
	v_mfma_f32_16x16x32_bf16 v[28:31], v[160:163], v[208:211], v[28:31]
	v_mfma_f32_16x16x32_bf16 v[24:27], v[168:171], v[208:211], v[24:27]
	v_mfma_f32_16x16x32_bf16 v[12:15], v[160:163], v[216:219], v[12:15]
	v_mfma_f32_16x16x32_bf16 v[8:11], v[168:171], v[216:219], v[8:11]
	v_mfma_f32_16x16x32_bf16 v[52:55], v[172:175], v[188:191], v[52:55]
	v_mfma_f32_16x16x32_bf16 v[48:51], v[180:183], v[188:191], v[48:51]
	v_mfma_f32_16x16x32_bf16 v[36:39], v[172:175], v[196:199], v[36:39]
	v_mfma_f32_16x16x32_bf16 v[32:35], v[180:183], v[196:199], v[32:35]
	v_mfma_f32_16x16x32_bf16 v[20:23], v[172:175], v[204:207], v[20:23]
	v_mfma_f32_16x16x32_bf16 v[16:19], v[180:183], v[204:207], v[16:19]
	v_mfma_f32_16x16x32_bf16 v[4:7], v[172:175], v[212:215], v[4:7]
	v_mfma_f32_16x16x32_bf16 v[0:3], v[180:183], v[212:215], v[0:3]
	v_mfma_f32_16x16x32_bf16 v[52:55], v[176:179], v[192:195], v[52:55]
	v_mfma_f32_16x16x32_bf16 v[48:51], v[184:187], v[192:195], v[48:51]
	v_mfma_f32_16x16x32_bf16 v[36:39], v[176:179], v[200:203], v[36:39]
	v_mfma_f32_16x16x32_bf16 v[32:35], v[184:187], v[200:203], v[32:35]
	v_mfma_f32_16x16x32_bf16 v[20:23], v[176:179], v[208:211], v[20:23]
	v_mfma_f32_16x16x32_bf16 v[16:19], v[184:187], v[208:211], v[16:19]
	v_mfma_f32_16x16x32_bf16 v[4:7], v[176:179], v[216:219], v[4:7]
	v_mfma_f32_16x16x32_bf16 v[0:3], v[184:187], v[216:219], v[0:3]
	s_setprio 0
	s_barrier
	s_add_i32 s92, s92, 2
	s_add_u32 s64, s64, 0x100
	s_addc_u32 s65, s65, 0
	s_add_u32 s90, s90, 0x100
	s_addc_u32 s91, s91, 0
	s_cmp_gt_u32 s92, 13
	s_cbranch_scc0 .LBB0_295
	s_and_b64 vcc, exec, s[14:15]
	s_cbranch_vccz .LBB0_298
	s_and_b64 vcc, exec, s[2:3]
	s_cbranch_vccnz .LBB0_298
	s_barrier
.LBB0_298:
	v_lshl_add_u32 v150, s0, 8, v152
	v_ashrrev_i32_e32 v151, 31, v150
	v_lshl_add_u64 v[146:147], v[150:151], 2, s[12:13]
	global_load_dword v159, v[146:147], off
	global_load_dword v200, v[146:147], off offset:64
	global_load_dword v201, v[146:147], off offset:128
	global_load_dword v202, v[146:147], off offset:192
	global_load_dword v203, v[146:147], off offset:512
	global_load_dword v204, v[146:147], off offset:576
	global_load_dword v205, v[146:147], off offset:640
	global_load_dword v206, v[146:147], off offset:704
	v_lshl_or_b32 v148, s1, 8, v154
	v_ashrrev_i32_e32 v149, 31, v148
	v_lshlrev_b64 v[164:165], 1, v[148:149]
	v_lshlrev_b64 v[162:163], 13, v[150:151]
	v_or_b32_e32 v160, 16, v150
	v_ashrrev_i32_e32 v161, 31, v160
	s_mov_b64 s[0:1], 0x100000
	s_mov_b32 s19, 0x100000
	s_waitcnt vmcnt(0)
	v_fmamk_f32 v148, v159, 0x3a800000, v158
	v_mul_f32_e32 v149, 0x4b800000, v148
	v_cmp_gt_f32_e32 vcc, s87, v148
	s_nop 1
	v_cndmask_b32_e32 v148, v148, v149, vcc
	v_rsq_f32_e32 v151, v148
	v_lshl_add_u64 v[148:149], s[8:9], 0, v[162:163]
	v_lshl_add_u64 v[148:149], v[148:149], 0, v[164:165]
	v_lshl_add_u64 v[162:163], v[160:161], 2, s[12:13]
	v_mul_f32_e32 v159, 0x45800000, v151
	v_cndmask_b32_e32 v166, v151, v159, vcc
	v_pk_mul_f32 v[126:127], v[126:127], v[166:167] op_sel_hi:[1,0]
	v_pk_mul_f32 v[124:125], v[124:125], v[166:167] op_sel_hi:[1,0]
	v_pk_mul_f32 v[122:123], v[122:123], v[166:167] op_sel_hi:[1,0]
	v_pk_mul_f32 v[120:121], v[120:121], v[166:167] op_sel_hi:[1,0]
	v_pk_mul_f32 v[118:119], v[118:119], v[166:167] op_sel_hi:[1,0]
	v_pk_mul_f32 v[116:117], v[116:117], v[166:167] op_sel_hi:[1,0]
	v_pk_mul_f32 v[168:169], v[114:115], v[166:167] op_sel_hi:[1,0]
	v_pk_mul_f32 v[166:167], v[112:113], v[166:167] op_sel_hi:[1,0]
	v_cvt_pk_bf16_f32 v112, v124, v125
	v_cvt_pk_bf16_f32 v113, v126, v127
	v_cvt_pk_bf16_f32 v114, v120, v121
	v_cvt_pk_bf16_f32 v115, v122, v123
	global_store_dwordx4 v[148:149], v[112:115], off
	s_nop 1
	v_cvt_pk_bf16_f32 v112, v116, v117
	v_cvt_pk_bf16_f32 v113, v118, v119
	v_cvt_pk_bf16_f32 v114, v166, v167
	v_cvt_pk_bf16_f32 v115, v168, v169
	global_store_dwordx4 v[148:149], v[112:115], off offset:256
	s_nop 0
	s_nop 0
	v_fmamk_f32 v116, v200, 0x3a800000, v158
	v_mul_f32_e32 v117, 0x4b800000, v116
	v_cmp_gt_f32_e32 vcc, s87, v116
	v_lshlrev_b64 v[114:115], 13, v[160:161]
	v_or_b32_e32 v112, 32, v150
	v_cndmask_b32_e32 v116, v116, v117, vcc
	v_rsq_f32_e32 v118, v116
	v_lshl_add_u64 v[114:115], s[8:9], 0, v[114:115]
	v_ashrrev_i32_e32 v113, 31, v112
	v_lshl_add_u64 v[114:115], v[114:115], 0, v[164:165]
	v_mul_f32_e32 v119, 0x45800000, v118
	v_cndmask_b32_e32 v118, v118, v119, vcc
	v_pk_mul_f32 v[110:111], v[110:111], v[118:119] op_sel_hi:[1,0]
	v_pk_mul_f32 v[108:109], v[108:109], v[118:119] op_sel_hi:[1,0]
	v_pk_mul_f32 v[106:107], v[106:107], v[118:119] op_sel_hi:[1,0]
	v_pk_mul_f32 v[104:105], v[104:105], v[118:119] op_sel_hi:[1,0]
	v_pk_mul_f32 v[102:103], v[102:103], v[118:119] op_sel_hi:[1,0]
	v_pk_mul_f32 v[100:101], v[100:101], v[118:119] op_sel_hi:[1,0]
	v_pk_mul_f32 v[120:121], v[98:99], v[118:119] op_sel_hi:[1,0]
	v_pk_mul_f32 v[118:119], v[96:97], v[118:119] op_sel_hi:[1,0]
	v_cvt_pk_bf16_f32 v96, v108, v109
	v_cvt_pk_bf16_f32 v97, v110, v111
	v_cvt_pk_bf16_f32 v98, v104, v105
	v_cvt_pk_bf16_f32 v99, v106, v107
	v_lshl_add_u64 v[116:117], v[112:113], 2, s[12:13]
	global_store_dwordx4 v[114:115], v[96:99], off
	s_nop 1
	v_cvt_pk_bf16_f32 v96, v100, v101
	v_cvt_pk_bf16_f32 v97, v102, v103
	v_cvt_pk_bf16_f32 v98, v118, v119
	v_cvt_pk_bf16_f32 v99, v120, v121
	global_store_dwordx4 v[114:115], v[96:99], off offset:256
	s_nop 0
	s_nop 0
	v_fmamk_f32 v100, v201, 0x3a800000, v158
	v_mul_f32_e32 v101, 0x4b800000, v100
	v_cmp_gt_f32_e32 vcc, s87, v100
	v_lshlrev_b64 v[98:99], 13, v[112:113]
	v_or_b32_e32 v96, 48, v150
	v_cndmask_b32_e32 v100, v100, v101, vcc
	v_rsq_f32_e32 v102, v100
	v_lshl_add_u64 v[98:99], s[8:9], 0, v[98:99]
	v_ashrrev_i32_e32 v97, 31, v96
	v_lshl_add_u64 v[98:99], v[98:99], 0, v[164:165]
	v_mul_f32_e32 v103, 0x45800000, v102
	v_cndmask_b32_e32 v102, v102, v103, vcc
	v_pk_mul_f32 v[94:95], v[94:95], v[102:103] op_sel_hi:[1,0]
	v_pk_mul_f32 v[92:93], v[92:93], v[102:103] op_sel_hi:[1,0]
	v_pk_mul_f32 v[90:91], v[90:91], v[102:103] op_sel_hi:[1,0]
	v_pk_mul_f32 v[88:89], v[88:89], v[102:103] op_sel_hi:[1,0]
	v_pk_mul_f32 v[86:87], v[86:87], v[102:103] op_sel_hi:[1,0]
	v_pk_mul_f32 v[84:85], v[84:85], v[102:103] op_sel_hi:[1,0]
	v_pk_mul_f32 v[104:105], v[82:83], v[102:103] op_sel_hi:[1,0]
	v_pk_mul_f32 v[102:103], v[80:81], v[102:103] op_sel_hi:[1,0]
	v_cvt_pk_bf16_f32 v80, v92, v93
	v_cvt_pk_bf16_f32 v81, v94, v95
	v_cvt_pk_bf16_f32 v82, v88, v89
	v_cvt_pk_bf16_f32 v83, v90, v91
	v_lshl_add_u64 v[100:101], v[96:97], 2, s[12:13]
	global_store_dwordx4 v[98:99], v[80:83], off
	s_nop 1
	v_cvt_pk_bf16_f32 v80, v84, v85
	v_cvt_pk_bf16_f32 v81, v86, v87
	v_cvt_pk_bf16_f32 v82, v102, v103
	v_cvt_pk_bf16_f32 v83, v104, v105
	global_store_dwordx4 v[98:99], v[80:83], off offset:256
	s_nop 0
	s_nop 0
	v_fmamk_f32 v80, v202, 0x3a800000, v158
	v_mul_f32_e32 v81, 0x4b800000, v80
	v_cmp_gt_f32_e32 vcc, s87, v80
	s_nop 1
	v_cndmask_b32_e32 v80, v80, v81, vcc
	v_rsq_f32_e32 v82, v80
	v_lshlrev_b64 v[80:81], 13, v[96:97]
	v_lshl_add_u64 v[80:81], s[8:9], 0, v[80:81]
	v_lshl_add_u64 v[80:81], v[80:81], 0, v[164:165]
	v_mul_f32_e32 v83, 0x45800000, v82
	v_cndmask_b32_e32 v82, v82, v83, vcc
	v_pk_mul_f32 v[78:79], v[78:79], v[82:83] op_sel_hi:[1,0]
	v_pk_mul_f32 v[76:77], v[76:77], v[82:83] op_sel_hi:[1,0]
	v_pk_mul_f32 v[74:75], v[74:75], v[82:83] op_sel_hi:[1,0]
	v_pk_mul_f32 v[72:73], v[72:73], v[82:83] op_sel_hi:[1,0]
	v_pk_mul_f32 v[70:71], v[70:71], v[82:83] op_sel_hi:[1,0]
	v_pk_mul_f32 v[68:69], v[68:69], v[82:83] op_sel_hi:[1,0]
	v_pk_mul_f32 v[84:85], v[66:67], v[82:83] op_sel_hi:[1,0]
	v_pk_mul_f32 v[82:83], v[64:65], v[82:83] op_sel_hi:[1,0]
	v_cvt_pk_bf16_f32 v64, v76, v77
	v_cvt_pk_bf16_f32 v65, v78, v79
	v_cvt_pk_bf16_f32 v66, v72, v73
	v_cvt_pk_bf16_f32 v67, v74, v75
	global_store_dwordx4 v[80:81], v[64:67], off
	s_nop 1
	v_cvt_pk_bf16_f32 v64, v68, v69
	v_cvt_pk_bf16_f32 v65, v70, v71
	v_cvt_pk_bf16_f32 v66, v82, v83
	v_cvt_pk_bf16_f32 v67, v84, v85
	global_store_dwordx4 v[80:81], v[64:67], off offset:256
	s_nop 0
	s_nop 0
	v_lshl_add_u64 v[64:65], v[148:149], 0, s[0:1]
	s_nop 0
	v_fmamk_f32 v66, v203, 0x3a800000, v158
	v_mul_f32_e32 v67, 0x4b800000, v66
	v_cmp_gt_f32_e32 vcc, s87, v66
	s_nop 1
	v_cndmask_b32_e32 v66, v66, v67, vcc
	v_rsq_f32_e32 v68, v66
	v_add_co_u32_e64 v66, s[0:1], s19, v148
	s_mov_b32 s19, 0x120000
	v_mul_f32_e32 v69, 0x45800000, v68
	v_cndmask_b32_e32 v68, v68, v69, vcc
	v_addc_co_u32_e64 v67, s[0:1], 0, v149, s[0:1]
	v_pk_mul_f32 v[62:63], v[62:63], v[68:69] op_sel_hi:[1,0]
	v_pk_mul_f32 v[60:61], v[60:61], v[68:69] op_sel_hi:[1,0]
	v_pk_mul_f32 v[58:59], v[58:59], v[68:69] op_sel_hi:[1,0]
	v_pk_mul_f32 v[56:57], v[56:57], v[68:69] op_sel_hi:[1,0]
	v_pk_mul_f32 v[54:55], v[54:55], v[68:69] op_sel_hi:[1,0]
	v_pk_mul_f32 v[52:53], v[52:53], v[68:69] op_sel_hi:[1,0]
	v_pk_mul_f32 v[70:71], v[50:51], v[68:69] op_sel_hi:[1,0]
	v_pk_mul_f32 v[68:69], v[48:49], v[68:69] op_sel_hi:[1,0]
	v_cvt_pk_bf16_f32 v48, v60, v61
	v_cvt_pk_bf16_f32 v49, v62, v63
	v_cvt_pk_bf16_f32 v50, v56, v57
	v_cvt_pk_bf16_f32 v51, v58, v59
	global_store_dwordx4 v[66:67], v[48:51], off
	s_mov_b64 s[0:1], 0x120000
	s_nop 0
	v_cvt_pk_bf16_f32 v48, v52, v53
	v_cvt_pk_bf16_f32 v49, v54, v55
	v_cvt_pk_bf16_f32 v50, v68, v69
	v_cvt_pk_bf16_f32 v51, v70, v71
	global_store_dwordx4 v[64:65], v[48:51], off offset:256
	s_nop 0
	s_nop 0
	v_lshl_add_u64 v[48:49], v[148:149], 0, s[0:1]
	s_nop 0
	v_fmamk_f32 v50, v204, 0x3a800000, v158
	v_mul_f32_e32 v51, 0x4b800000, v50
	v_cmp_gt_f32_e32 vcc, s87, v50
	s_nop 1
	v_cndmask_b32_e32 v50, v50, v51, vcc
	v_rsq_f32_e32 v52, v50
	v_add_co_u32_e64 v50, s[0:1], s19, v148
	v_mul_f32_e32 v53, 0x45800000, v52
	v_cndmask_b32_e32 v52, v52, v53, vcc
	v_addc_co_u32_e64 v51, s[0:1], 0, v149, s[0:1]
	v_pk_mul_f32 v[46:47], v[46:47], v[52:53] op_sel_hi:[1,0]
	v_pk_mul_f32 v[44:45], v[44:45], v[52:53] op_sel_hi:[1,0]
	v_pk_mul_f32 v[42:43], v[42:43], v[52:53] op_sel_hi:[1,0]
	v_pk_mul_f32 v[40:41], v[40:41], v[52:53] op_sel_hi:[1,0]
	v_pk_mul_f32 v[38:39], v[38:39], v[52:53] op_sel_hi:[1,0]
	v_pk_mul_f32 v[36:37], v[36:37], v[52:53] op_sel_hi:[1,0]
	v_pk_mul_f32 v[54:55], v[34:35], v[52:53] op_sel_hi:[1,0]
	v_pk_mul_f32 v[52:53], v[32:33], v[52:53] op_sel_hi:[1,0]
	v_cvt_pk_bf16_f32 v32, v44, v45
	v_cvt_pk_bf16_f32 v33, v46, v47
	v_cvt_pk_bf16_f32 v34, v40, v41
	v_cvt_pk_bf16_f32 v35, v42, v43
	global_store_dwordx4 v[50:51], v[32:35], off
	s_mov_b64 s[0:1], 0x140000
	s_nop 0
	v_cvt_pk_bf16_f32 v32, v36, v37
	v_cvt_pk_bf16_f32 v33, v38, v39
	v_cvt_pk_bf16_f32 v34, v52, v53
	v_cvt_pk_bf16_f32 v35, v54, v55
	global_store_dwordx4 v[48:49], v[32:35], off offset:256
	s_nop 0
	s_nop 0
	v_lshl_add_u64 v[32:33], v[148:149], 0, s[0:1]
	s_nop 0
	v_fmamk_f32 v34, v205, 0x3a800000, v158
	v_mul_f32_e32 v35, 0x4b800000, v34
	v_cmp_gt_f32_e32 vcc, s87, v34
	s_nop 1
	v_cndmask_b32_e32 v34, v34, v35, vcc
	v_rsq_f32_e32 v36, v34
	v_add_co_u32_e64 v34, s[0:1], s88, v148
	v_mul_f32_e32 v37, 0x45800000, v36
	v_cndmask_b32_e32 v36, v36, v37, vcc
	v_addc_co_u32_e64 v35, s[0:1], 0, v149, s[0:1]
	v_pk_mul_f32 v[30:31], v[30:31], v[36:37] op_sel_hi:[1,0]
	v_pk_mul_f32 v[28:29], v[28:29], v[36:37] op_sel_hi:[1,0]
	v_pk_mul_f32 v[26:27], v[26:27], v[36:37] op_sel_hi:[1,0]
	v_pk_mul_f32 v[24:25], v[24:25], v[36:37] op_sel_hi:[1,0]
	v_pk_mul_f32 v[22:23], v[22:23], v[36:37] op_sel_hi:[1,0]
	v_pk_mul_f32 v[20:21], v[20:21], v[36:37] op_sel_hi:[1,0]
	v_pk_mul_f32 v[38:39], v[18:19], v[36:37] op_sel_hi:[1,0]
	v_pk_mul_f32 v[36:37], v[16:17], v[36:37] op_sel_hi:[1,0]
	v_cvt_pk_bf16_f32 v16, v28, v29
	v_cvt_pk_bf16_f32 v17, v30, v31
	v_cvt_pk_bf16_f32 v18, v24, v25
	v_cvt_pk_bf16_f32 v19, v26, v27
	global_store_dwordx4 v[34:35], v[16:19], off
	s_andn2_b64 vcc, exec, s[2:3]
	s_nop 0
	v_cvt_pk_bf16_f32 v16, v20, v21
	v_cvt_pk_bf16_f32 v17, v22, v23
	v_cvt_pk_bf16_f32 v18, v36, v37
	v_cvt_pk_bf16_f32 v19, v38, v39
	global_store_dwordx4 v[32:33], v[16:19], off offset:256
	s_nop 0
	s_nop 0
	v_lshl_add_u64 v[16:17], v[148:149], 0, s[16:17]
	s_nop 0
	v_fmamk_f32 v18, v206, 0x3a800000, v158
	v_mul_f32_e32 v19, 0x4b800000, v18
	v_cmp_gt_f32_e64 s[0:1], s87, v18
	s_nop 1
	v_cndmask_b32_e64 v18, v18, v19, s[0:1]
	v_rsq_f32_e32 v20, v18
	v_add_co_u32_e64 v18, s[2:3], s89, v148
	v_mul_f32_e32 v21, 0x45800000, v20
	v_cndmask_b32_e64 v20, v20, v21, s[0:1]
	v_addc_co_u32_e64 v19, s[2:3], 0, v149, s[2:3]
	v_pk_mul_f32 v[14:15], v[14:15], v[20:21] op_sel_hi:[1,0]
	v_pk_mul_f32 v[12:13], v[12:13], v[20:21] op_sel_hi:[1,0]
	v_pk_mul_f32 v[10:11], v[10:11], v[20:21] op_sel_hi:[1,0]
	v_pk_mul_f32 v[8:9], v[8:9], v[20:21] op_sel_hi:[1,0]
	v_pk_mul_f32 v[6:7], v[6:7], v[20:21] op_sel_hi:[1,0]
	v_pk_mul_f32 v[4:5], v[4:5], v[20:21] op_sel_hi:[1,0]
	v_pk_mul_f32 v[22:23], v[2:3], v[20:21] op_sel_hi:[1,0]
	v_pk_mul_f32 v[20:21], v[0:1], v[20:21] op_sel_hi:[1,0]
	v_cvt_pk_bf16_f32 v0, v12, v13
	v_cvt_pk_bf16_f32 v1, v14, v15
	v_cvt_pk_bf16_f32 v2, v8, v9
	v_cvt_pk_bf16_f32 v3, v10, v11
	s_mov_b64 s[0:1], -1
	global_store_dwordx4 v[18:19], v[0:3], off
	s_nop 1
	v_cvt_pk_bf16_f32 v0, v4, v5
	v_cvt_pk_bf16_f32 v1, v6, v7
	v_cvt_pk_bf16_f32 v2, v20, v21
	v_cvt_pk_bf16_f32 v3, v22, v23
	global_store_dwordx4 v[16:17], v[0:3], off offset:256
	s_cbranch_vccnz .LBB0_287
	s_andn2_b64 vcc, exec, s[6:7]
	s_cbranch_vccnz .LBB0_286
	s_branch .LBB0_286

.LBB0_1342:
	ds_read_b128 v[146:149], v154
	ds_read_b128 v[158:161], v154 offset:1024
	ds_read_b128 v[162:165], v154 offset:2048
	ds_read_b128 v[166:169], v154 offset:3072
	ds_read_b128 v[170:173], v155
	ds_read_b128 v[174:177], v155 offset:1024
	ds_read_b128 v[178:181], v155 offset:2048
	ds_read_b128 v[182:185], v155 offset:3072
	s_add_u32 s23, s40, 0xfffc0080
	s_addc_u32 s33, s41, -1
	s_cmp_eq_u32 s67, 12
	s_cselect_b32 s45, s19, s33
	s_cselect_b32 s44, s20, s23
	s_cselect_b32 s43, s17, s66
	s_cselect_b32 s42, s21, s65
	s_add_i32 m0, s52, 0xc000
	ds_read_b128 v[186:189], v156
	ds_read_b128 v[190:193], v156 offset:1024
	ds_read_b128 v[194:197], v156 offset:2048
	ds_read_b128 v[198:201], v156 offset:3072
	ds_read_b128 v[202:205], v156 offset:4096
	ds_read_b128 v[206:209], v156 offset:5120
	ds_read_b128 v[210:213], v156 offset:6144
	ds_read_b128 v[214:217], v156 offset:7168
	global_load_lds_dwordx4 v138, s[40:41]
	s_add_i32 m0, s52, 0xe000
	s_nop 0
	global_load_lds_dwordx4 v140, s[40:41]
	s_waitcnt vmcnt(8)
	s_waitcnt lgkmcnt(0)
	s_barrier
	s_setprio 1
	v_mfma_f32_16x16x32_bf16 v[116:119], v[146:149], v[186:189], v[116:119]
	v_mfma_f32_16x16x32_bf16 v[112:115], v[162:165], v[186:189], v[112:115]
	v_mfma_f32_16x16x32_bf16 v[100:103], v[146:149], v[194:197], v[100:103]
	v_mfma_f32_16x16x32_bf16 v[96:99], v[162:165], v[194:197], v[96:99]
	v_mfma_f32_16x16x32_bf16 v[84:87], v[146:149], v[202:205], v[84:87]
	v_mfma_f32_16x16x32_bf16 v[80:83], v[162:165], v[202:205], v[80:83]
	v_mfma_f32_16x16x32_bf16 v[72:75], v[146:149], v[210:213], v[72:75]
	v_mfma_f32_16x16x32_bf16 v[64:67], v[162:165], v[210:213], v[64:67]
	v_mfma_f32_16x16x32_bf16 v[116:119], v[158:161], v[190:193], v[116:119]
	v_mfma_f32_16x16x32_bf16 v[112:115], v[166:169], v[190:193], v[112:115]
	v_mfma_f32_16x16x32_bf16 v[100:103], v[158:161], v[198:201], v[100:103]
	v_mfma_f32_16x16x32_bf16 v[96:99], v[166:169], v[198:201], v[96:99]
	v_mfma_f32_16x16x32_bf16 v[84:87], v[158:161], v[206:209], v[84:87]
	v_mfma_f32_16x16x32_bf16 v[80:83], v[166:169], v[206:209], v[80:83]
	v_mfma_f32_16x16x32_bf16 v[72:75], v[158:161], v[214:217], v[72:75]
	v_mfma_f32_16x16x32_bf16 v[64:67], v[166:169], v[214:217], v[64:67]
	v_mfma_f32_16x16x32_bf16 v[124:127], v[170:173], v[186:189], v[124:127]
	v_mfma_f32_16x16x32_bf16 v[120:123], v[178:181], v[186:189], v[120:123]
	v_mfma_f32_16x16x32_bf16 v[108:111], v[170:173], v[194:197], v[108:111]
	v_mfma_f32_16x16x32_bf16 v[104:107], v[178:181], v[194:197], v[104:107]
	v_mfma_f32_16x16x32_bf16 v[92:95], v[170:173], v[202:205], v[92:95]
	v_mfma_f32_16x16x32_bf16 v[88:91], v[178:181], v[202:205], v[88:91]
	v_mfma_f32_16x16x32_bf16 v[76:79], v[170:173], v[210:213], v[76:79]
	v_mfma_f32_16x16x32_bf16 v[68:71], v[178:181], v[210:213], v[68:71]
	v_mfma_f32_16x16x32_bf16 v[124:127], v[174:177], v[190:193], v[124:127]
	v_mfma_f32_16x16x32_bf16 v[120:123], v[182:185], v[190:193], v[120:123]
	v_mfma_f32_16x16x32_bf16 v[108:111], v[174:177], v[198:201], v[108:111]
	v_mfma_f32_16x16x32_bf16 v[104:107], v[182:185], v[198:201], v[104:107]
	v_mfma_f32_16x16x32_bf16 v[92:95], v[174:177], v[206:209], v[92:95]
	v_mfma_f32_16x16x32_bf16 v[88:91], v[182:185], v[206:209], v[88:91]
	v_mfma_f32_16x16x32_bf16 v[76:79], v[174:177], v[214:217], v[76:79]
	v_mfma_f32_16x16x32_bf16 v[68:71], v[182:185], v[214:217], v[68:71]
	s_setprio 0
	s_barrier
	s_add_i32 s23, s61, s50
	s_mov_b32 m0, s23
	ds_read_b128 v[186:189], v156 offset:16384
	ds_read_b128 v[190:193], v156 offset:17408
	ds_read_b128 v[194:197], v156 offset:18432
	ds_read_b128 v[198:201], v156 offset:19456
	ds_read_b128 v[202:205], v156 offset:20480
	ds_read_b128 v[206:209], v156 offset:21504
	ds_read_b128 v[210:213], v156 offset:22528
	ds_read_b128 v[214:217], v156 offset:23552
	global_load_lds_dwordx4 v132, s[42:43]
	s_add_i32 m0, s23, 0x2000
	s_add_u32 s68, s42, 0x40000
	s_addc_u32 s69, s43, 0
	s_add_i32 s23, s62, s50
	global_load_lds_dwordx4 v136, s[42:43]
	s_mov_b32 m0, s23
	s_add_u32 s98, s42, s12
	s_addc_u32 s99, s43, s13
	global_load_lds_dwordx4 v132, s[68:69]
	s_add_i32 m0, s23, 0x2000
	s_add_u32 s100, s44, s12
	s_addc_u32 s101, s45, s13
	global_load_lds_dwordx4 v136, s[68:69]
	s_mov_b32 m0, s52
	s_nop 0
	global_load_lds_dwordx4 v130, s[44:45]
	s_mov_b32 m0, s53
	s_nop 0
	global_load_lds_dwordx4 v134, s[44:45]
	s_waitcnt vmcnt(8)
	s_waitcnt lgkmcnt(0)
	s_barrier
	s_setprio 1
	v_mfma_f32_16x16x32_bf16 v[56:59], v[146:149], v[186:189], v[56:59]
	v_mfma_f32_16x16x32_bf16 v[48:51], v[162:165], v[186:189], v[48:51]
	v_mfma_f32_16x16x32_bf16 v[40:43], v[146:149], v[194:197], v[40:43]
	v_mfma_f32_16x16x32_bf16 v[32:35], v[162:165], v[194:197], v[32:35]
	v_mfma_f32_16x16x32_bf16 v[24:27], v[146:149], v[202:205], v[24:27]
	v_mfma_f32_16x16x32_bf16 v[16:19], v[162:165], v[202:205], v[16:19]
	v_mfma_f32_16x16x32_bf16 v[8:11], v[146:149], v[210:213], v[8:11]
	v_mfma_f32_16x16x32_bf16 v[0:3], v[162:165], v[210:213], v[0:3]
	v_mfma_f32_16x16x32_bf16 v[56:59], v[158:161], v[190:193], v[56:59]
	v_mfma_f32_16x16x32_bf16 v[48:51], v[166:169], v[190:193], v[48:51]
	v_mfma_f32_16x16x32_bf16 v[40:43], v[158:161], v[198:201], v[40:43]
	v_mfma_f32_16x16x32_bf16 v[32:35], v[166:169], v[198:201], v[32:35]
	v_mfma_f32_16x16x32_bf16 v[24:27], v[158:161], v[206:209], v[24:27]
	v_mfma_f32_16x16x32_bf16 v[16:19], v[166:169], v[206:209], v[16:19]
	v_mfma_f32_16x16x32_bf16 v[8:11], v[158:161], v[214:217], v[8:11]
	v_mfma_f32_16x16x32_bf16 v[0:3], v[166:169], v[214:217], v[0:3]
	v_mfma_f32_16x16x32_bf16 v[60:63], v[170:173], v[186:189], v[60:63]
	v_mfma_f32_16x16x32_bf16 v[52:55], v[178:181], v[186:189], v[52:55]
	v_mfma_f32_16x16x32_bf16 v[44:47], v[170:173], v[194:197], v[44:47]
	v_mfma_f32_16x16x32_bf16 v[36:39], v[178:181], v[194:197], v[36:39]
	v_mfma_f32_16x16x32_bf16 v[28:31], v[170:173], v[202:205], v[28:31]
	v_mfma_f32_16x16x32_bf16 v[20:23], v[178:181], v[202:205], v[20:23]
	v_mfma_f32_16x16x32_bf16 v[12:15], v[170:173], v[210:213], v[12:15]
	v_mfma_f32_16x16x32_bf16 v[4:7], v[178:181], v[210:213], v[4:7]
	v_mfma_f32_16x16x32_bf16 v[60:63], v[174:177], v[190:193], v[60:63]
	v_mfma_f32_16x16x32_bf16 v[52:55], v[182:185], v[190:193], v[52:55]
	v_mfma_f32_16x16x32_bf16 v[44:47], v[174:177], v[198:201], v[44:47]
	v_mfma_f32_16x16x32_bf16 v[36:39], v[182:185], v[198:201], v[36:39]
	v_mfma_f32_16x16x32_bf16 v[28:31], v[174:177], v[206:209], v[28:31]
	v_mfma_f32_16x16x32_bf16 v[20:23], v[182:185], v[206:209], v[20:23]
	v_mfma_f32_16x16x32_bf16 v[12:15], v[174:177], v[214:217], v[12:15]
	v_mfma_f32_16x16x32_bf16 v[4:7], v[182:185], v[214:217], v[4:7]
	s_setprio 0
	s_barrier
	s_add_i32 s23, 0, 0x18000
	s_add_i32 s33, 0, 0x1c000
	v_add_u32_e32 v166, s23, v152
	v_add_u32_e32 v182, s33, v152
	ds_read_b128 v[146:149], v166
	ds_read_b128 v[158:161], v166 offset:1024
	ds_read_b128 v[162:165], v166 offset:2048
	ds_read_b128 v[166:169], v166 offset:3072
	ds_read_b128 v[170:173], v182
	ds_read_b128 v[174:177], v182 offset:1024
	ds_read_b128 v[178:181], v182 offset:2048
	ds_read_b128 v[182:185], v182 offset:3072
	s_add_u32 s44, s44, 0x40000
	s_addc_u32 s45, s45, 0
	s_mov_b32 m0, s54
	ds_read_b128 v[186:189], v156 offset:32768
	ds_read_b128 v[190:193], v156 offset:33792
	ds_read_b128 v[194:197], v156 offset:34816
	ds_read_b128 v[198:201], v156 offset:35840
	ds_read_b128 v[202:205], v156 offset:36864
	ds_read_b128 v[206:209], v156 offset:37888
	ds_read_b128 v[210:213], v156 offset:38912
	ds_read_b128 v[214:217], v156 offset:39936
	global_load_lds_dwordx4 v130, s[44:45]
	s_mov_b32 m0, s55
	s_nop 0
	global_load_lds_dwordx4 v134, s[44:45]
	s_waitcnt vmcnt(8)
	s_waitcnt lgkmcnt(0)
	s_barrier
	s_setprio 1
	v_mfma_f32_16x16x32_bf16 v[116:119], v[146:149], v[186:189], v[116:119]
	v_mfma_f32_16x16x32_bf16 v[112:115], v[162:165], v[186:189], v[112:115]
	v_mfma_f32_16x16x32_bf16 v[100:103], v[146:149], v[194:197], v[100:103]
	v_mfma_f32_16x16x32_bf16 v[96:99], v[162:165], v[194:197], v[96:99]
	v_mfma_f32_16x16x32_bf16 v[84:87], v[146:149], v[202:205], v[84:87]
	v_mfma_f32_16x16x32_bf16 v[80:83], v[162:165], v[202:205], v[80:83]
	v_mfma_f32_16x16x32_bf16 v[72:75], v[146:149], v[210:213], v[72:75]
	v_mfma_f32_16x16x32_bf16 v[64:67], v[162:165], v[210:213], v[64:67]
	v_mfma_f32_16x16x32_bf16 v[116:119], v[158:161], v[190:193], v[116:119]
	v_mfma_f32_16x16x32_bf16 v[112:115], v[166:169], v[190:193], v[112:115]
	v_mfma_f32_16x16x32_bf16 v[100:103], v[158:161], v[198:201], v[100:103]
	v_mfma_f32_16x16x32_bf16 v[96:99], v[166:169], v[198:201], v[96:99]
	v_mfma_f32_16x16x32_bf16 v[84:87], v[158:161], v[206:209], v[84:87]
	v_mfma_f32_16x16x32_bf16 v[80:83], v[166:169], v[206:209], v[80:83]
	v_mfma_f32_16x16x32_bf16 v[72:75], v[158:161], v[214:217], v[72:75]
	v_mfma_f32_16x16x32_bf16 v[64:67], v[166:169], v[214:217], v[64:67]
	v_mfma_f32_16x16x32_bf16 v[124:127], v[170:173], v[186:189], v[124:127]
	v_mfma_f32_16x16x32_bf16 v[120:123], v[178:181], v[186:189], v[120:123]
	v_mfma_f32_16x16x32_bf16 v[108:111], v[170:173], v[194:197], v[108:111]
	v_mfma_f32_16x16x32_bf16 v[104:107], v[178:181], v[194:197], v[104:107]
	v_mfma_f32_16x16x32_bf16 v[92:95], v[170:173], v[202:205], v[92:95]
	v_mfma_f32_16x16x32_bf16 v[88:91], v[178:181], v[202:205], v[88:91]
	v_mfma_f32_16x16x32_bf16 v[76:79], v[170:173], v[210:213], v[76:79]
	v_mfma_f32_16x16x32_bf16 v[68:71], v[178:181], v[210:213], v[68:71]
	v_mfma_f32_16x16x32_bf16 v[124:127], v[174:177], v[190:193], v[124:127]
	v_mfma_f32_16x16x32_bf16 v[120:123], v[182:185], v[190:193], v[120:123]
	v_mfma_f32_16x16x32_bf16 v[108:111], v[174:177], v[198:201], v[108:111]
	v_mfma_f32_16x16x32_bf16 v[104:107], v[182:185], v[198:201], v[104:107]
	v_mfma_f32_16x16x32_bf16 v[92:95], v[174:177], v[206:209], v[92:95]
	v_mfma_f32_16x16x32_bf16 v[88:91], v[182:185], v[206:209], v[88:91]
	v_mfma_f32_16x16x32_bf16 v[76:79], v[174:177], v[214:217], v[76:79]
	v_mfma_f32_16x16x32_bf16 v[68:71], v[182:185], v[214:217], v[68:71]
	s_setprio 0
	s_barrier
	s_add_i32 s23, s23, s50
	s_mov_b32 m0, s23
	ds_read_b128 v[186:189], v156 offset:49152
	ds_read_b128 v[190:193], v156 offset:50176
	ds_read_b128 v[194:197], v156 offset:51200
	ds_read_b128 v[198:201], v156 offset:52224
	ds_read_b128 v[202:205], v156 offset:53248
	ds_read_b128 v[206:209], v156 offset:54272
	ds_read_b128 v[210:213], v156 offset:55296
	ds_read_b128 v[214:217], v156 offset:56320
	global_load_lds_dwordx4 v132, s[98:99]
	s_add_i32 m0, s23, 0x2000
	s_add_u32 s42, s42, 0x40080
	s_addc_u32 s43, s43, 0
	s_add_i32 s23, s33, s50
	global_load_lds_dwordx4 v136, s[98:99]
	s_mov_b32 m0, s23
	s_nop 0
	global_load_lds_dwordx4 v132, s[42:43]
	s_add_i32 m0, s23, 0x2000
	s_nop 0
	global_load_lds_dwordx4 v136, s[42:43]
	s_mov_b32 m0, s58
	s_nop 0
	global_load_lds_dwordx4 v130, s[100:101]
	s_mov_b32 m0, s59
	s_nop 0
	global_load_lds_dwordx4 v134, s[100:101]
	s_waitcnt vmcnt(8)
	s_waitcnt lgkmcnt(0)
	s_barrier
	s_setprio 1
	v_mfma_f32_16x16x32_bf16 v[56:59], v[146:149], v[186:189], v[56:59]
	v_mfma_f32_16x16x32_bf16 v[48:51], v[162:165], v[186:189], v[48:51]
	v_mfma_f32_16x16x32_bf16 v[40:43], v[146:149], v[194:197], v[40:43]
	v_mfma_f32_16x16x32_bf16 v[32:35], v[162:165], v[194:197], v[32:35]
	v_mfma_f32_16x16x32_bf16 v[24:27], v[146:149], v[202:205], v[24:27]
	v_mfma_f32_16x16x32_bf16 v[16:19], v[162:165], v[202:205], v[16:19]
	v_mfma_f32_16x16x32_bf16 v[8:11], v[146:149], v[210:213], v[8:11]
	v_mfma_f32_16x16x32_bf16 v[0:3], v[162:165], v[210:213], v[0:3]
	v_mfma_f32_16x16x32_bf16 v[56:59], v[158:161], v[190:193], v[56:59]
	v_mfma_f32_16x16x32_bf16 v[48:51], v[166:169], v[190:193], v[48:51]
	v_mfma_f32_16x16x32_bf16 v[40:43], v[158:161], v[198:201], v[40:43]
	v_mfma_f32_16x16x32_bf16 v[32:35], v[166:169], v[198:201], v[32:35]
	v_mfma_f32_16x16x32_bf16 v[24:27], v[158:161], v[206:209], v[24:27]
	v_mfma_f32_16x16x32_bf16 v[16:19], v[166:169], v[206:209], v[16:19]
	v_mfma_f32_16x16x32_bf16 v[8:11], v[158:161], v[214:217], v[8:11]
	v_mfma_f32_16x16x32_bf16 v[0:3], v[166:169], v[214:217], v[0:3]
	v_mfma_f32_16x16x32_bf16 v[60:63], v[170:173], v[186:189], v[60:63]
	v_mfma_f32_16x16x32_bf16 v[52:55], v[178:181], v[186:189], v[52:55]
	v_mfma_f32_16x16x32_bf16 v[44:47], v[170:173], v[194:197], v[44:47]
	v_mfma_f32_16x16x32_bf16 v[36:39], v[178:181], v[194:197], v[36:39]
	v_mfma_f32_16x16x32_bf16 v[28:31], v[170:173], v[202:205], v[28:31]
	v_mfma_f32_16x16x32_bf16 v[20:23], v[178:181], v[202:205], v[20:23]
	v_mfma_f32_16x16x32_bf16 v[12:15], v[170:173], v[210:213], v[12:15]
	v_mfma_f32_16x16x32_bf16 v[4:7], v[178:181], v[210:213], v[4:7]
	v_mfma_f32_16x16x32_bf16 v[60:63], v[174:177], v[190:193], v[60:63]
	v_mfma_f32_16x16x32_bf16 v[52:55], v[182:185], v[190:193], v[52:55]
	v_mfma_f32_16x16x32_bf16 v[44:47], v[174:177], v[198:201], v[44:47]
	v_mfma_f32_16x16x32_bf16 v[36:39], v[182:185], v[198:201], v[36:39]
	v_mfma_f32_16x16x32_bf16 v[28:31], v[174:177], v[206:209], v[28:31]
	v_mfma_f32_16x16x32_bf16 v[20:23], v[182:185], v[206:209], v[20:23]
	v_mfma_f32_16x16x32_bf16 v[12:15], v[174:177], v[214:217], v[12:15]
	v_mfma_f32_16x16x32_bf16 v[4:7], v[182:185], v[214:217], v[4:7]
	s_setprio 0
	s_barrier
	s_add_i32 s67, s67, 2
	s_add_u32 s40, s40, 0x100
	s_addc_u32 s41, s41, 0
	s_add_u32 s65, s65, 0x100
	s_addc_u32 s66, s66, 0
	s_cmp_gt_u32 s67, 13
	s_cbranch_scc0 .LBB0_1342
	s_and_b64 vcc, exec, s[14:15]
	s_cbranch_vccz .LBB0_1345
	s_and_b64 vcc, exec, s[2:3]
	s_cbranch_vccnz .LBB0_1345
	s_barrier
.LBB0_1345:
	v_lshl_add_u32 v146, s0, 8, v150
	v_ashrrev_i32_e32 v147, 31, v146
	v_lshl_add_u64 v[148:149], v[146:147], 2, s[10:11]
	global_load_dword v147, v[148:149], off
	global_load_dword v200, v[148:149], off offset:64
	global_load_dword v201, v[148:149], off offset:128
	global_load_dword v202, v[148:149], off offset:192
	global_load_dword v203, v[148:149], off offset:512
	global_load_dword v204, v[148:149], off offset:576
	global_load_dword v205, v[148:149], off offset:640
	global_load_dword v206, v[148:149], off offset:704
	v_lshl_or_b32 v158, s1, 7, v153
	v_ashrrev_i32_e32 v159, 31, v158
	v_mov_b32_e32 v162, v122
	v_mov_b32_e32 v163, v114
	v_mov_b32_e32 v114, v123
	v_lshlrev_b64 v[122:123], 1, v[158:159]
	v_mov_b32_e32 v160, v124
	v_mov_b32_e32 v161, v116
	v_mov_b32_e32 v116, v125
	v_mov_b32_e32 v124, v126
	v_mov_b32_e32 v125, v118
	v_mov_b32_e32 v118, v127
	v_mov_b32_e32 v126, v120
	v_mov_b32_e32 v127, v112
	v_mov_b32_e32 v112, v121
	v_mov_b64_e32 v[120:121], s[8:9]
	v_or_b32_e32 v166, 16, v146
	v_mad_i64_i32 v[164:165], s[0:1], v146, s64, v[120:121]
	v_ashrrev_i32_e32 v167, 31, v166
	s_waitcnt vmcnt(0)
	v_fmamk_f32 v147, v147, 0x3a800000, v157
	v_mul_f32_e32 v158, 0x4b800000, v147
	v_cmp_gt_f32_e32 vcc, s63, v147
	s_nop 1
	v_cndmask_b32_e32 v147, v147, v158, vcc
	v_rsq_f32_e32 v147, v147
	v_lshl_add_u64 v[158:159], v[164:165], 0, v[122:123]
	v_lshl_add_u64 v[164:165], v[166:167], 2, s[10:11]
	v_mul_f32_e32 v167, 0x45800000, v147
	v_cndmask_b32_e32 v168, v147, v167, vcc
	v_pk_mul_f32 v[114:115], v[114:115], v[168:169] op_sel_hi:[1,0]
	v_pk_mul_f32 v[160:161], v[160:161], v[168:169] op_sel_hi:[1,0]
	v_pk_mul_f32 v[116:117], v[116:117], v[168:169] op_sel_hi:[1,0]
	v_pk_mul_f32 v[124:125], v[124:125], v[168:169] op_sel_hi:[1,0]
	v_pk_mul_f32 v[118:119], v[118:119], v[168:169] op_sel_hi:[1,0]
	v_pk_mul_f32 v[126:127], v[126:127], v[168:169] op_sel_hi:[1,0]
	v_pk_mul_f32 v[112:113], v[112:113], v[168:169] op_sel_hi:[1,0]
	v_pk_mul_f32 v[162:163], v[162:163], v[168:169] op_sel_hi:[1,0]
	v_mul_f32_e32 v173, 0xbfb8aa3b, v115
	v_mul_f32_e32 v147, 0xbfb8aa3b, v161
	v_mul_f32_e32 v167, 0xbfb8aa3b, v117
	v_mul_f32_e32 v168, 0xbfb8aa3b, v125
	v_mul_f32_e32 v169, 0xbfb8aa3b, v119
	v_mul_f32_e32 v170, 0xbfb8aa3b, v127
	v_mul_f32_e32 v171, 0xbfb8aa3b, v113
	v_mul_f32_e32 v172, 0xbfb8aa3b, v163
	v_exp_f32_e32 v173, v173
	v_exp_f32_e32 v147, v147
	v_exp_f32_e32 v167, v167
	v_exp_f32_e32 v168, v168
	v_exp_f32_e32 v169, v169
	v_exp_f32_e32 v170, v170
	v_exp_f32_e32 v171, v171
	v_exp_f32_e32 v172, v172
	v_add_f32_e32 v173, 1.0, v173
	v_add_f32_e32 v147, 1.0, v147
	v_add_f32_e32 v167, 1.0, v167
	v_add_f32_e32 v168, 1.0, v168
	v_add_f32_e32 v169, 1.0, v169
	v_add_f32_e32 v170, 1.0, v170
	v_add_f32_e32 v171, 1.0, v171
	v_add_f32_e32 v172, 1.0, v172
	v_rcp_f32_e32 v173, v173
	v_rcp_f32_e32 v147, v147
	v_rcp_f32_e32 v167, v167
	v_rcp_f32_e32 v168, v168
	v_rcp_f32_e32 v169, v169
	v_rcp_f32_e32 v170, v170
	v_rcp_f32_e32 v171, v171
	v_rcp_f32_e32 v172, v172
	v_mul_f32_e32 v115, v115, v173
	v_mul_f32_e32 v147, v161, v147
	v_mul_f32_e32 v117, v117, v167
	v_mul_f32_e32 v125, v125, v168
	v_mul_f32_e32 v119, v119, v169
	v_mul_f32_e32 v127, v127, v170
	v_mul_f32_e32 v113, v113, v171
	v_mul_f32_e32 v161, v163, v172
	v_mul_f32_e32 v115, v114, v115
	v_mul_f32_e32 v147, v160, v147
	v_mul_f32_e32 v116, v116, v117
	v_mul_f32_e32 v117, v124, v125
	v_mul_f32_e32 v118, v118, v119
	v_mul_f32_e32 v119, v126, v127
	v_mul_f32_e32 v124, v112, v113
	v_mul_f32_e32 v125, v162, v161
	v_cvt_pk_bf16_f32 v112, v147, v116
	v_cvt_pk_bf16_f32 v113, v117, v118
	v_cvt_pk_bf16_f32 v114, v119, v124
	v_cvt_pk_bf16_f32 v115, v125, v115
	global_store_dwordx4 v[158:159], v[112:115], off
	s_nop 0
	s_nop 0
	v_mov_b32_e32 v113, v100
	v_mov_b32_e32 v100, v109
	v_mov_b32_e32 v109, v102
	v_mov_b32_e32 v102, v111
	v_mov_b32_e32 v111, v96
	v_mov_b32_e32 v96, v105
	v_mov_b32_e32 v105, v98
	v_mov_b32_e32 v98, v107
	v_mov_b32_e32 v112, v108
	v_mov_b32_e32 v108, v110
	v_mov_b32_e32 v110, v104
	v_mov_b32_e32 v104, v106
	v_or_b32_e32 v106, 32, v146
	v_mad_i64_i32 v[114:115], s[0:1], v166, s64, v[120:121]
	v_lshl_add_u64 v[114:115], v[114:115], 0, v[122:123]
	s_nop 0
	v_fmamk_f32 v107, v200, 0x3a800000, v157
	v_mul_f32_e32 v116, 0x4b800000, v107
	v_cmp_gt_f32_e32 vcc, s63, v107
	s_nop 1
	v_cndmask_b32_e32 v107, v107, v116, vcc
	v_rsq_f32_e32 v118, v107
	v_ashrrev_i32_e32 v107, 31, v106
	v_lshl_add_u64 v[116:117], v[106:107], 2, s[10:11]
	v_mul_f32_e32 v107, 0x45800000, v118
	v_cndmask_b32_e32 v118, v118, v107, vcc
	v_pk_mul_f32 v[98:99], v[98:99], v[118:119] op_sel_hi:[1,0]
	v_pk_mul_f32 v[112:113], v[112:113], v[118:119] op_sel_hi:[1,0]
	v_pk_mul_f32 v[100:101], v[100:101], v[118:119] op_sel_hi:[1,0]
	v_pk_mul_f32 v[108:109], v[108:109], v[118:119] op_sel_hi:[1,0]
	v_pk_mul_f32 v[102:103], v[102:103], v[118:119] op_sel_hi:[1,0]
	v_pk_mul_f32 v[110:111], v[110:111], v[118:119] op_sel_hi:[1,0]
	v_pk_mul_f32 v[96:97], v[96:97], v[118:119] op_sel_hi:[1,0]
	v_pk_mul_f32 v[104:105], v[104:105], v[118:119] op_sel_hi:[1,0]
	v_mul_f32_e32 v147, 0xbfb8aa3b, v99
	v_mul_f32_e32 v107, 0xbfb8aa3b, v113
	v_mul_f32_e32 v118, 0xbfb8aa3b, v101
	v_mul_f32_e32 v119, 0xbfb8aa3b, v109
	v_mul_f32_e32 v124, 0xbfb8aa3b, v103
	v_mul_f32_e32 v125, 0xbfb8aa3b, v111
	v_mul_f32_e32 v126, 0xbfb8aa3b, v97
	v_mul_f32_e32 v127, 0xbfb8aa3b, v105
	v_exp_f32_e32 v147, v147
	v_exp_f32_e32 v107, v107
	v_exp_f32_e32 v118, v118
	v_exp_f32_e32 v119, v119
	v_exp_f32_e32 v124, v124
	v_exp_f32_e32 v125, v125
	v_exp_f32_e32 v126, v126
	v_exp_f32_e32 v127, v127
	v_add_f32_e32 v147, 1.0, v147
	v_add_f32_e32 v107, 1.0, v107
	v_add_f32_e32 v118, 1.0, v118
	v_add_f32_e32 v119, 1.0, v119
	v_add_f32_e32 v124, 1.0, v124
	v_add_f32_e32 v125, 1.0, v125
	v_add_f32_e32 v126, 1.0, v126
	v_add_f32_e32 v127, 1.0, v127
	v_rcp_f32_e32 v147, v147
	v_rcp_f32_e32 v107, v107
	v_rcp_f32_e32 v118, v118
	v_rcp_f32_e32 v119, v119
	v_rcp_f32_e32 v124, v124
	v_rcp_f32_e32 v125, v125
	v_rcp_f32_e32 v126, v126
	v_rcp_f32_e32 v127, v127
	v_mul_f32_e32 v99, v99, v147
	v_mul_f32_e32 v107, v113, v107
	v_mul_f32_e32 v101, v101, v118
	v_mul_f32_e32 v109, v109, v119
	v_mul_f32_e32 v103, v103, v124
	v_mul_f32_e32 v111, v111, v125
	v_mul_f32_e32 v97, v97, v126
	v_mul_f32_e32 v105, v105, v127
	v_mul_f32_e32 v99, v98, v99
	v_mul_f32_e32 v107, v112, v107
	v_mul_f32_e32 v100, v100, v101
	v_mul_f32_e32 v101, v108, v109
	v_mul_f32_e32 v102, v102, v103
	v_mul_f32_e32 v103, v110, v111
	v_mul_f32_e32 v108, v96, v97
	v_mul_f32_e32 v104, v104, v105
	v_cvt_pk_bf16_f32 v96, v107, v100
	v_cvt_pk_bf16_f32 v97, v101, v102
	v_cvt_pk_bf16_f32 v98, v103, v108
	v_cvt_pk_bf16_f32 v99, v104, v99
	global_store_dwordx4 v[114:115], v[96:99], off
	s_nop 0
	s_nop 0
	v_mov_b32_e32 v97, v84
	v_mov_b32_e32 v84, v93
	v_mov_b32_e32 v93, v86
	v_mov_b32_e32 v86, v95
	v_mov_b32_e32 v95, v80
	v_mov_b32_e32 v80, v89
	v_mov_b32_e32 v89, v82
	v_mov_b32_e32 v82, v91
	v_mov_b32_e32 v96, v92
	v_mov_b32_e32 v92, v94
	v_mov_b32_e32 v94, v88
	v_mov_b32_e32 v88, v90
	v_or_b32_e32 v90, 48, v146
	v_mad_i64_i32 v[98:99], s[0:1], v106, s64, v[120:121]
	v_lshl_add_u64 v[98:99], v[98:99], 0, v[122:123]
	s_nop 0
	v_fmamk_f32 v91, v201, 0x3a800000, v157
	v_mul_f32_e32 v100, 0x4b800000, v91
	v_cmp_gt_f32_e32 vcc, s63, v91
	s_nop 1
	v_cndmask_b32_e32 v91, v91, v100, vcc
	v_rsq_f32_e32 v102, v91
	v_ashrrev_i32_e32 v91, 31, v90
	v_lshl_add_u64 v[100:101], v[90:91], 2, s[10:11]
	v_mul_f32_e32 v91, 0x45800000, v102
	v_cndmask_b32_e32 v102, v102, v91, vcc
	v_pk_mul_f32 v[82:83], v[82:83], v[102:103] op_sel_hi:[1,0]
	v_pk_mul_f32 v[96:97], v[96:97], v[102:103] op_sel_hi:[1,0]
	v_pk_mul_f32 v[84:85], v[84:85], v[102:103] op_sel_hi:[1,0]
	v_pk_mul_f32 v[92:93], v[92:93], v[102:103] op_sel_hi:[1,0]
	v_pk_mul_f32 v[86:87], v[86:87], v[102:103] op_sel_hi:[1,0]
	v_pk_mul_f32 v[94:95], v[94:95], v[102:103] op_sel_hi:[1,0]
	v_pk_mul_f32 v[80:81], v[80:81], v[102:103] op_sel_hi:[1,0]
	v_pk_mul_f32 v[88:89], v[88:89], v[102:103] op_sel_hi:[1,0]
	v_mul_f32_e32 v108, 0xbfb8aa3b, v83
	v_mul_f32_e32 v91, 0xbfb8aa3b, v97
	v_mul_f32_e32 v102, 0xbfb8aa3b, v85
	v_mul_f32_e32 v103, 0xbfb8aa3b, v93
	v_mul_f32_e32 v104, 0xbfb8aa3b, v87
	v_mul_f32_e32 v105, 0xbfb8aa3b, v95
	v_mul_f32_e32 v106, 0xbfb8aa3b, v81
	v_mul_f32_e32 v107, 0xbfb8aa3b, v89
	v_exp_f32_e32 v108, v108
	v_exp_f32_e32 v91, v91
	v_exp_f32_e32 v102, v102
	v_exp_f32_e32 v103, v103
	v_exp_f32_e32 v104, v104
	v_exp_f32_e32 v105, v105
	v_exp_f32_e32 v106, v106
	v_exp_f32_e32 v107, v107
	v_add_f32_e32 v108, 1.0, v108
	v_add_f32_e32 v91, 1.0, v91
	v_add_f32_e32 v102, 1.0, v102
	v_add_f32_e32 v103, 1.0, v103
	v_add_f32_e32 v104, 1.0, v104
	v_add_f32_e32 v105, 1.0, v105
	v_add_f32_e32 v106, 1.0, v106
	v_add_f32_e32 v107, 1.0, v107
	v_rcp_f32_e32 v108, v108
	v_rcp_f32_e32 v91, v91
	v_rcp_f32_e32 v102, v102
	v_rcp_f32_e32 v103, v103
	v_rcp_f32_e32 v104, v104
	v_rcp_f32_e32 v105, v105
	v_rcp_f32_e32 v106, v106
	v_rcp_f32_e32 v107, v107
	v_mul_f32_e32 v83, v83, v108
	v_mul_f32_e32 v91, v97, v91
	v_mul_f32_e32 v85, v85, v102
	v_mul_f32_e32 v93, v93, v103
	v_mul_f32_e32 v87, v87, v104
	v_mul_f32_e32 v95, v95, v105
	v_mul_f32_e32 v81, v81, v106
	v_mul_f32_e32 v89, v89, v107
	v_mul_f32_e32 v83, v82, v83
	v_mul_f32_e32 v91, v96, v91
	v_mul_f32_e32 v84, v84, v85
	v_mul_f32_e32 v85, v92, v93
	v_mul_f32_e32 v86, v86, v87
	v_mul_f32_e32 v87, v94, v95
	v_mul_f32_e32 v92, v80, v81
	v_mul_f32_e32 v88, v88, v89
	v_cvt_pk_bf16_f32 v80, v91, v84
	v_cvt_pk_bf16_f32 v81, v85, v86
	v_cvt_pk_bf16_f32 v82, v87, v92
	v_cvt_pk_bf16_f32 v83, v88, v83
	global_store_dwordx4 v[98:99], v[80:83], off
	s_nop 0
	s_nop 0
	v_mov_b32_e32 v80, v76
	v_mov_b32_e32 v76, v78
	v_mov_b32_e32 v78, v68
	v_mov_b32_e32 v68, v70
	v_mov_b32_e32 v81, v72
	v_mov_b32_e32 v72, v77
	v_mov_b32_e32 v77, v74
	v_mov_b32_e32 v74, v79
	v_mov_b32_e32 v79, v64
	v_mov_b32_e32 v64, v69
	v_mov_b32_e32 v69, v66
	v_mov_b32_e32 v66, v71
	s_nop 0
	v_fmamk_f32 v70, v202, 0x3a800000, v157
	v_mul_f32_e32 v71, 0x4b800000, v70
	v_cmp_gt_f32_e32 vcc, s63, v70
	s_nop 1
	v_cndmask_b32_e32 v70, v70, v71, vcc
	v_rsq_f32_e32 v82, v70
	v_mad_i64_i32 v[70:71], s[0:1], v90, s64, v[120:121]
	v_lshl_add_u64 v[70:71], v[70:71], 0, v[122:123]
	v_mul_f32_e32 v83, 0x45800000, v82
	v_cndmask_b32_e32 v82, v82, v83, vcc
	v_pk_mul_f32 v[66:67], v[66:67], v[82:83] op_sel_hi:[1,0]
	v_pk_mul_f32 v[80:81], v[80:81], v[82:83] op_sel_hi:[1,0]
	v_pk_mul_f32 v[72:73], v[72:73], v[82:83] op_sel_hi:[1,0]
	v_pk_mul_f32 v[76:77], v[76:77], v[82:83] op_sel_hi:[1,0]
	v_pk_mul_f32 v[74:75], v[74:75], v[82:83] op_sel_hi:[1,0]
	v_pk_mul_f32 v[78:79], v[78:79], v[82:83] op_sel_hi:[1,0]
	v_pk_mul_f32 v[64:65], v[64:65], v[82:83] op_sel_hi:[1,0]
	v_pk_mul_f32 v[68:69], v[68:69], v[82:83] op_sel_hi:[1,0]
	v_mul_f32_e32 v89, 0xbfb8aa3b, v67
	v_mul_f32_e32 v82, 0xbfb8aa3b, v81
	v_mul_f32_e32 v83, 0xbfb8aa3b, v73
	v_mul_f32_e32 v84, 0xbfb8aa3b, v77
	v_mul_f32_e32 v85, 0xbfb8aa3b, v75
	v_mul_f32_e32 v86, 0xbfb8aa3b, v79
	v_mul_f32_e32 v87, 0xbfb8aa3b, v65
	v_mul_f32_e32 v88, 0xbfb8aa3b, v69
	v_exp_f32_e32 v89, v89
	v_exp_f32_e32 v82, v82
	v_exp_f32_e32 v83, v83
	v_exp_f32_e32 v84, v84
	v_exp_f32_e32 v85, v85
	v_exp_f32_e32 v86, v86
	v_exp_f32_e32 v87, v87
	v_exp_f32_e32 v88, v88
	v_add_f32_e32 v89, 1.0, v89
	v_add_f32_e32 v82, 1.0, v82
	v_add_f32_e32 v83, 1.0, v83
	v_add_f32_e32 v84, 1.0, v84
	v_add_f32_e32 v85, 1.0, v85
	v_add_f32_e32 v86, 1.0, v86
	v_add_f32_e32 v87, 1.0, v87
	v_add_f32_e32 v88, 1.0, v88
	v_rcp_f32_e32 v89, v89
	v_rcp_f32_e32 v82, v82
	v_rcp_f32_e32 v83, v83
	v_rcp_f32_e32 v84, v84
	v_rcp_f32_e32 v85, v85
	v_rcp_f32_e32 v86, v86
	v_rcp_f32_e32 v87, v87
	v_rcp_f32_e32 v88, v88
	v_mul_f32_e32 v67, v67, v89
	v_mul_f32_e32 v81, v81, v82
	v_mul_f32_e32 v73, v73, v83
	v_mul_f32_e32 v77, v77, v84
	v_mul_f32_e32 v75, v75, v85
	v_mul_f32_e32 v79, v79, v86
	v_mul_f32_e32 v65, v65, v87
	v_mul_f32_e32 v69, v69, v88
	v_mul_f32_e32 v67, v66, v67
	v_mul_f32_e32 v80, v80, v81
	v_mul_f32_e32 v72, v72, v73
	v_mul_f32_e32 v73, v76, v77
	v_mul_f32_e32 v74, v74, v75
	v_mul_f32_e32 v75, v78, v79
	v_mul_f32_e32 v76, v64, v65
	v_mul_f32_e32 v68, v68, v69
	v_cvt_pk_bf16_f32 v64, v80, v72
	v_cvt_pk_bf16_f32 v65, v73, v74
	v_cvt_pk_bf16_f32 v66, v75, v76
	v_cvt_pk_bf16_f32 v67, v68, v67
	global_store_dwordx4 v[70:71], v[64:67], off
	s_nop 0
	s_nop 0
	v_mov_b32_e32 v65, v56
	v_mov_b32_e32 v56, v61
	v_mov_b32_e32 v61, v58
	v_mov_b32_e32 v58, v63
	v_mov_b32_e32 v63, v48
	v_mov_b32_e32 v48, v53
	v_mov_b32_e32 v53, v50
	v_mov_b32_e32 v50, v55
	v_mov_b32_e32 v64, v60
	v_mov_b32_e32 v60, v62
	v_mov_b32_e32 v62, v52
	v_mov_b32_e32 v52, v54
	v_add_u32_e32 v54, 0x80, v146
	s_nop 0
	v_fmamk_f32 v55, v203, 0x3a800000, v157
	v_mul_f32_e32 v66, 0x4b800000, v55
	v_cmp_gt_f32_e32 vcc, s63, v55
	s_nop 1
	v_cndmask_b32_e32 v55, v55, v66, vcc
	v_rsq_f32_e32 v66, v55
	v_mad_i64_i32 v[54:55], s[0:1], v54, s64, v[120:121]
	v_lshl_add_u64 v[54:55], v[54:55], 0, v[122:123]
	v_mul_f32_e32 v67, 0x45800000, v66
	v_cndmask_b32_e32 v66, v66, v67, vcc
	v_pk_mul_f32 v[50:51], v[50:51], v[66:67] op_sel_hi:[1,0]
	v_pk_mul_f32 v[64:65], v[64:65], v[66:67] op_sel_hi:[1,0]
	v_pk_mul_f32 v[56:57], v[56:57], v[66:67] op_sel_hi:[1,0]
	v_pk_mul_f32 v[60:61], v[60:61], v[66:67] op_sel_hi:[1,0]
	v_pk_mul_f32 v[58:59], v[58:59], v[66:67] op_sel_hi:[1,0]
	v_pk_mul_f32 v[62:63], v[62:63], v[66:67] op_sel_hi:[1,0]
	v_pk_mul_f32 v[48:49], v[48:49], v[66:67] op_sel_hi:[1,0]
	v_pk_mul_f32 v[52:53], v[52:53], v[66:67] op_sel_hi:[1,0]
	v_mul_f32_e32 v73, 0xbfb8aa3b, v51
	v_mul_f32_e32 v66, 0xbfb8aa3b, v65
	v_mul_f32_e32 v67, 0xbfb8aa3b, v57
	v_mul_f32_e32 v68, 0xbfb8aa3b, v61
	v_mul_f32_e32 v69, 0xbfb8aa3b, v59
	v_mul_f32_e32 v70, 0xbfb8aa3b, v63
	v_mul_f32_e32 v71, 0xbfb8aa3b, v49
	v_mul_f32_e32 v72, 0xbfb8aa3b, v53
	v_exp_f32_e32 v73, v73
	v_exp_f32_e32 v66, v66
	v_exp_f32_e32 v67, v67
	v_exp_f32_e32 v68, v68
	v_exp_f32_e32 v69, v69
	v_exp_f32_e32 v70, v70
	v_exp_f32_e32 v71, v71
	v_exp_f32_e32 v72, v72
	v_add_f32_e32 v73, 1.0, v73
	v_add_f32_e32 v66, 1.0, v66
	v_add_f32_e32 v67, 1.0, v67
	v_add_f32_e32 v68, 1.0, v68
	v_add_f32_e32 v69, 1.0, v69
	v_add_f32_e32 v70, 1.0, v70
	v_add_f32_e32 v71, 1.0, v71
	v_add_f32_e32 v72, 1.0, v72
	v_rcp_f32_e32 v73, v73
	v_rcp_f32_e32 v66, v66
	v_rcp_f32_e32 v67, v67
	v_rcp_f32_e32 v68, v68
	v_rcp_f32_e32 v69, v69
	v_rcp_f32_e32 v70, v70
	v_rcp_f32_e32 v71, v71
	v_rcp_f32_e32 v72, v72
	v_mul_f32_e32 v51, v51, v73
	v_mul_f32_e32 v65, v65, v66
	v_mul_f32_e32 v57, v57, v67
	v_mul_f32_e32 v61, v61, v68
	v_mul_f32_e32 v59, v59, v69
	v_mul_f32_e32 v63, v63, v70
	v_mul_f32_e32 v49, v49, v71
	v_mul_f32_e32 v53, v53, v72
	v_mul_f32_e32 v51, v50, v51
	v_mul_f32_e32 v64, v64, v65
	v_mul_f32_e32 v56, v56, v57
	v_mul_f32_e32 v57, v60, v61
	v_mul_f32_e32 v58, v58, v59
	v_mul_f32_e32 v59, v62, v63
	v_mul_f32_e32 v60, v48, v49
	v_mul_f32_e32 v52, v52, v53
	v_cvt_pk_bf16_f32 v48, v64, v56
	v_cvt_pk_bf16_f32 v49, v57, v58
	v_cvt_pk_bf16_f32 v50, v59, v60
	v_cvt_pk_bf16_f32 v51, v52, v51
	global_store_dwordx4 v[54:55], v[48:51], off
	s_nop 0
	s_nop 0
	v_mov_b32_e32 v49, v40
	v_mov_b32_e32 v40, v45
	v_mov_b32_e32 v45, v42
	v_mov_b32_e32 v42, v47
	v_mov_b32_e32 v47, v32
	v_mov_b32_e32 v32, v37
	v_mov_b32_e32 v37, v34
	v_mov_b32_e32 v34, v39
	v_mov_b32_e32 v48, v44
	v_mov_b32_e32 v44, v46
	v_mov_b32_e32 v46, v36
	v_mov_b32_e32 v36, v38
	v_add_u32_e32 v38, 0x90, v146
	s_nop 0
	v_fmamk_f32 v39, v204, 0x3a800000, v157
	v_mul_f32_e32 v50, 0x4b800000, v39
	v_cmp_gt_f32_e32 vcc, s63, v39
	s_nop 1
	v_cndmask_b32_e32 v39, v39, v50, vcc
	v_rsq_f32_e32 v50, v39
	v_mad_i64_i32 v[38:39], s[0:1], v38, s64, v[120:121]
	v_lshl_add_u64 v[38:39], v[38:39], 0, v[122:123]
	v_mul_f32_e32 v51, 0x45800000, v50
	v_cndmask_b32_e32 v50, v50, v51, vcc
	v_pk_mul_f32 v[34:35], v[34:35], v[50:51] op_sel_hi:[1,0]
	v_pk_mul_f32 v[48:49], v[48:49], v[50:51] op_sel_hi:[1,0]
	v_pk_mul_f32 v[40:41], v[40:41], v[50:51] op_sel_hi:[1,0]
	v_pk_mul_f32 v[44:45], v[44:45], v[50:51] op_sel_hi:[1,0]
	v_pk_mul_f32 v[42:43], v[42:43], v[50:51] op_sel_hi:[1,0]
	v_pk_mul_f32 v[46:47], v[46:47], v[50:51] op_sel_hi:[1,0]
	v_pk_mul_f32 v[32:33], v[32:33], v[50:51] op_sel_hi:[1,0]
	v_pk_mul_f32 v[36:37], v[36:37], v[50:51] op_sel_hi:[1,0]
	v_mul_f32_e32 v57, 0xbfb8aa3b, v35
	v_mul_f32_e32 v50, 0xbfb8aa3b, v49
	v_mul_f32_e32 v51, 0xbfb8aa3b, v41
	v_mul_f32_e32 v52, 0xbfb8aa3b, v45
	v_mul_f32_e32 v53, 0xbfb8aa3b, v43
	v_mul_f32_e32 v54, 0xbfb8aa3b, v47
	v_mul_f32_e32 v55, 0xbfb8aa3b, v33
	v_mul_f32_e32 v56, 0xbfb8aa3b, v37
	v_exp_f32_e32 v57, v57
	v_exp_f32_e32 v50, v50
	v_exp_f32_e32 v51, v51
	v_exp_f32_e32 v52, v52
	v_exp_f32_e32 v53, v53
	v_exp_f32_e32 v54, v54
	v_exp_f32_e32 v55, v55
	v_exp_f32_e32 v56, v56
	v_add_f32_e32 v57, 1.0, v57
	v_add_f32_e32 v50, 1.0, v50
	v_add_f32_e32 v51, 1.0, v51
	v_add_f32_e32 v52, 1.0, v52
	v_add_f32_e32 v53, 1.0, v53
	v_add_f32_e32 v54, 1.0, v54
	v_add_f32_e32 v55, 1.0, v55
	v_add_f32_e32 v56, 1.0, v56
	v_rcp_f32_e32 v57, v57
	v_rcp_f32_e32 v50, v50
	v_rcp_f32_e32 v51, v51
	v_rcp_f32_e32 v52, v52
	v_rcp_f32_e32 v53, v53
	v_rcp_f32_e32 v54, v54
	v_rcp_f32_e32 v55, v55
	v_rcp_f32_e32 v56, v56
	v_mul_f32_e32 v35, v35, v57
	v_mul_f32_e32 v49, v49, v50
	v_mul_f32_e32 v41, v41, v51
	v_mul_f32_e32 v45, v45, v52
	v_mul_f32_e32 v43, v43, v53
	v_mul_f32_e32 v47, v47, v54
	v_mul_f32_e32 v33, v33, v55
	v_mul_f32_e32 v37, v37, v56
	v_mul_f32_e32 v35, v34, v35
	v_mul_f32_e32 v48, v48, v49
	v_mul_f32_e32 v40, v40, v41
	v_mul_f32_e32 v41, v44, v45
	v_mul_f32_e32 v42, v42, v43
	v_mul_f32_e32 v43, v46, v47
	v_mul_f32_e32 v44, v32, v33
	v_mul_f32_e32 v36, v36, v37
	v_cvt_pk_bf16_f32 v32, v48, v40
	v_cvt_pk_bf16_f32 v33, v41, v42
	v_cvt_pk_bf16_f32 v34, v43, v44
	v_cvt_pk_bf16_f32 v35, v36, v35
	global_store_dwordx4 v[38:39], v[32:35], off
	s_nop 0
	s_nop 0
	v_mov_b32_e32 v33, v24
	v_mov_b32_e32 v24, v29
	v_mov_b32_e32 v29, v26
	v_mov_b32_e32 v26, v31
	v_mov_b32_e32 v31, v16
	v_mov_b32_e32 v16, v21
	v_mov_b32_e32 v21, v18
	v_mov_b32_e32 v18, v23
	v_mov_b32_e32 v32, v28
	v_mov_b32_e32 v28, v30
	v_mov_b32_e32 v30, v20
	v_mov_b32_e32 v20, v22
	v_add_u32_e32 v22, 0xa0, v146
	s_nop 0
	v_fmamk_f32 v23, v205, 0x3a800000, v157
	v_mul_f32_e32 v34, 0x4b800000, v23
	v_cmp_gt_f32_e32 vcc, s63, v23
	s_nop 1
	v_cndmask_b32_e32 v23, v23, v34, vcc
	v_rsq_f32_e32 v34, v23
	v_mad_i64_i32 v[22:23], s[0:1], v22, s64, v[120:121]
	v_lshl_add_u64 v[22:23], v[22:23], 0, v[122:123]
	v_mul_f32_e32 v35, 0x45800000, v34
	v_cndmask_b32_e32 v34, v34, v35, vcc
	v_pk_mul_f32 v[18:19], v[18:19], v[34:35] op_sel_hi:[1,0]
	v_pk_mul_f32 v[32:33], v[32:33], v[34:35] op_sel_hi:[1,0]
	v_pk_mul_f32 v[24:25], v[24:25], v[34:35] op_sel_hi:[1,0]
	v_pk_mul_f32 v[28:29], v[28:29], v[34:35] op_sel_hi:[1,0]
	v_pk_mul_f32 v[26:27], v[26:27], v[34:35] op_sel_hi:[1,0]
	v_pk_mul_f32 v[30:31], v[30:31], v[34:35] op_sel_hi:[1,0]
	v_pk_mul_f32 v[16:17], v[16:17], v[34:35] op_sel_hi:[1,0]
	v_pk_mul_f32 v[20:21], v[20:21], v[34:35] op_sel_hi:[1,0]
	v_mul_f32_e32 v41, 0xbfb8aa3b, v19
	v_mul_f32_e32 v34, 0xbfb8aa3b, v33
	v_mul_f32_e32 v35, 0xbfb8aa3b, v25
	v_mul_f32_e32 v36, 0xbfb8aa3b, v29
	v_mul_f32_e32 v37, 0xbfb8aa3b, v27
	v_mul_f32_e32 v38, 0xbfb8aa3b, v31
	v_mul_f32_e32 v39, 0xbfb8aa3b, v17
	v_mul_f32_e32 v40, 0xbfb8aa3b, v21
	v_exp_f32_e32 v41, v41
	v_exp_f32_e32 v34, v34
	v_exp_f32_e32 v35, v35
	v_exp_f32_e32 v36, v36
	v_exp_f32_e32 v37, v37
	v_exp_f32_e32 v38, v38
	v_exp_f32_e32 v39, v39
	v_exp_f32_e32 v40, v40
	v_add_f32_e32 v41, 1.0, v41
	v_add_f32_e32 v34, 1.0, v34
	v_add_f32_e32 v35, 1.0, v35
	v_add_f32_e32 v36, 1.0, v36
	v_add_f32_e32 v37, 1.0, v37
	v_add_f32_e32 v38, 1.0, v38
	v_add_f32_e32 v39, 1.0, v39
	v_add_f32_e32 v40, 1.0, v40
	v_rcp_f32_e32 v41, v41
	v_rcp_f32_e32 v34, v34
	v_rcp_f32_e32 v35, v35
	v_rcp_f32_e32 v36, v36
	v_rcp_f32_e32 v37, v37
	v_rcp_f32_e32 v38, v38
	v_rcp_f32_e32 v39, v39
	v_rcp_f32_e32 v40, v40
	v_mul_f32_e32 v19, v19, v41
	v_mul_f32_e32 v33, v33, v34
	v_mul_f32_e32 v25, v25, v35
	v_mul_f32_e32 v29, v29, v36
	v_mul_f32_e32 v27, v27, v37
	v_mul_f32_e32 v31, v31, v38
	v_mul_f32_e32 v17, v17, v39
	v_mul_f32_e32 v21, v21, v40
	v_mul_f32_e32 v19, v18, v19
	v_mul_f32_e32 v32, v32, v33
	v_mul_f32_e32 v24, v24, v25
	v_mul_f32_e32 v25, v28, v29
	v_mul_f32_e32 v26, v26, v27
	v_mul_f32_e32 v27, v30, v31
	v_mul_f32_e32 v28, v16, v17
	v_mul_f32_e32 v20, v20, v21
	v_cvt_pk_bf16_f32 v16, v32, v24
	v_cvt_pk_bf16_f32 v17, v25, v26
	v_cvt_pk_bf16_f32 v18, v27, v28
	v_cvt_pk_bf16_f32 v19, v20, v19
	global_store_dwordx4 v[22:23], v[16:19], off
	s_nop 0
	s_andn2_b64 vcc, exec, s[2:3]
	v_mov_b32_e32 v17, v8
	v_mov_b32_e32 v8, v13
	v_mov_b32_e32 v13, v10
	v_mov_b32_e32 v10, v15
	v_mov_b32_e32 v15, v0
	v_mov_b32_e32 v0, v5
	v_mov_b32_e32 v5, v2
	v_mov_b32_e32 v2, v7
	v_mov_b32_e32 v16, v12
	v_mov_b32_e32 v12, v14
	v_mov_b32_e32 v14, v4
	v_mov_b32_e32 v4, v6
	v_add_u32_e32 v6, 0xb0, v146
	s_nop 0
	v_fmamk_f32 v7, v206, 0x3a800000, v157
	v_mul_f32_e32 v18, 0x4b800000, v7
	v_cmp_gt_f32_e64 s[0:1], s63, v7
	s_nop 1
	v_cndmask_b32_e64 v7, v7, v18, s[0:1]
	v_rsq_f32_e32 v18, v7
	v_mad_i64_i32 v[6:7], s[20:21], v6, s64, v[120:121]
	v_lshl_add_u64 v[6:7], v[6:7], 0, v[122:123]
	v_mul_f32_e32 v19, 0x45800000, v18
	v_cndmask_b32_e64 v18, v18, v19, s[0:1]
	v_pk_mul_f32 v[2:3], v[2:3], v[18:19] op_sel_hi:[1,0]
	v_pk_mul_f32 v[16:17], v[16:17], v[18:19] op_sel_hi:[1,0]
	v_pk_mul_f32 v[8:9], v[8:9], v[18:19] op_sel_hi:[1,0]
	v_pk_mul_f32 v[12:13], v[12:13], v[18:19] op_sel_hi:[1,0]
	v_pk_mul_f32 v[10:11], v[10:11], v[18:19] op_sel_hi:[1,0]
	v_pk_mul_f32 v[14:15], v[14:15], v[18:19] op_sel_hi:[1,0]
	v_pk_mul_f32 v[0:1], v[0:1], v[18:19] op_sel_hi:[1,0]
	v_pk_mul_f32 v[4:5], v[4:5], v[18:19] op_sel_hi:[1,0]
	v_mul_f32_e32 v25, 0xbfb8aa3b, v3
	v_mul_f32_e32 v18, 0xbfb8aa3b, v17
	v_mul_f32_e32 v19, 0xbfb8aa3b, v9
	v_mul_f32_e32 v20, 0xbfb8aa3b, v13
	v_mul_f32_e32 v21, 0xbfb8aa3b, v11
	v_mul_f32_e32 v22, 0xbfb8aa3b, v15
	v_mul_f32_e32 v23, 0xbfb8aa3b, v1
	v_mul_f32_e32 v24, 0xbfb8aa3b, v5
	v_exp_f32_e32 v25, v25
	v_exp_f32_e32 v18, v18
	v_exp_f32_e32 v19, v19
	v_exp_f32_e32 v20, v20
	v_exp_f32_e32 v21, v21
	v_exp_f32_e32 v22, v22
	v_exp_f32_e32 v23, v23
	v_exp_f32_e32 v24, v24
	v_add_f32_e32 v25, 1.0, v25
	v_add_f32_e32 v18, 1.0, v18
	v_add_f32_e32 v19, 1.0, v19
	v_add_f32_e32 v20, 1.0, v20
	v_add_f32_e32 v21, 1.0, v21
	v_add_f32_e32 v22, 1.0, v22
	v_add_f32_e32 v23, 1.0, v23
	v_add_f32_e32 v24, 1.0, v24
	v_rcp_f32_e32 v25, v25
	v_rcp_f32_e32 v18, v18
	v_rcp_f32_e32 v19, v19
	v_rcp_f32_e32 v20, v20
	v_rcp_f32_e32 v21, v21
	v_rcp_f32_e32 v22, v22
	v_rcp_f32_e32 v23, v23
	v_rcp_f32_e32 v24, v24
	v_mul_f32_e32 v3, v3, v25
	v_mul_f32_e32 v17, v17, v18
	v_mul_f32_e32 v9, v9, v19
	v_mul_f32_e32 v13, v13, v20
	v_mul_f32_e32 v11, v11, v21
	v_mul_f32_e32 v15, v15, v22
	v_mul_f32_e32 v1, v1, v23
	v_mul_f32_e32 v5, v5, v24
	v_mul_f32_e32 v3, v2, v3
	s_mov_b64 s[0:1], -1
	v_mul_f32_e32 v16, v16, v17
	v_mul_f32_e32 v8, v8, v9
	v_mul_f32_e32 v9, v12, v13
	v_mul_f32_e32 v10, v10, v11
	v_mul_f32_e32 v11, v14, v15
	v_mul_f32_e32 v12, v0, v1
	v_mul_f32_e32 v4, v4, v5
	v_cvt_pk_bf16_f32 v0, v16, v8
	v_cvt_pk_bf16_f32 v1, v9, v10
	v_cvt_pk_bf16_f32 v2, v11, v12
	v_cvt_pk_bf16_f32 v3, v4, v3
	global_store_dwordx4 v[6:7], v[0:3], off
	s_cbranch_vccnz .LBB0_1334
	s_andn2_b64 vcc, exec, s[6:7]
	s_cbranch_vccnz .LBB0_1333
	s_branch .LBB0_1333
